# EpiIn (gates,u/q/k): SSQ loads hoisted; EpiBranch<0>,<1>: gate/merged loads software-pipelined through a rotating register pool with counted vmcnt
# speedup vs baseline: 1.0663x; 1.0070x over previous
.LBB0_614:
	s_andn2_b64 vcc, exec, s[0:1]
	s_cbranch_vccnz .LBB0_616
	v_ashrrev_i32_e32 v169, 31, v168
	v_lshl_add_u32 v144, s68, 8, v204
	v_lshlrev_b64 v[170:171], 12, v[168:169]
	v_lshl_add_u64 v[172:173], s[60:61], 0, v[170:171]
	v_lshlrev_b64 v[170:171], 1, v[144:145]
	v_lshl_add_u64 v[132:133], v[144:145], 2, s[92:93]
	v_lshl_add_u64 v[176:177], v[172:173], 0, v[170:171]
	v_lshl_add_u64 v[172:173], v[168:169], 4, s[48:49]
	global_load_dwordx4 v[136:139], v[132:133], off offset:16
	global_load_dwordx4 v[140:143], v[132:133], off
	global_load_dwordx4 v[128:131], v[132:133], off offset:528
	s_nop 0
	global_load_dwordx4 v[132:135], v[132:133], off offset:512
	s_nop 0
	global_load_dwordx4 v[210:213], v[172:173], off offset:256
	global_load_dwordx4 v[214:217], v[172:173], off offset:512
	global_load_dwordx4 v[218:221], v[172:173], off offset:768
	global_load_dwordx4 v[222:225], v[172:173], off offset:2048
	global_load_dwordx4 v[226:229], v[172:173], off offset:2304
	global_load_dwordx4 v[230:233], v[172:173], off offset:2560
	global_load_dwordx4 v[234:237], v[172:173], off offset:2816
	global_load_dwordx4 v[172:175], v[172:173], off
	s_waitcnt vmcnt(0)
	v_mov_b32_e32 v178, v173
	v_mov_b32_e32 v179, v174
	v_mov_b32_e32 v173, v175
	v_pk_add_f32 v[172:173], v[178:179], v[172:173]
	s_nop 0
	v_add_f32_e32 v144, v172, v173
	v_fmamk_f32 v144, v144, 0x3a800000, v184
	v_rsq_f32_e32 v144, v144
	s_nop 0
	v_pk_fma_f32 v[172:173], v[126:127], v[144:145], v[142:143] op_sel_hi:[1,0,1]
	s_nop 0
	v_mul_f32_e32 v172, 0xbfb8aa3b, v172
	v_exp_f32_e32 v172, v172
	v_pk_fma_f32 v[174:175], v[124:125], v[144:145], v[140:141] op_sel_hi:[1,0,1]
	v_pk_fma_f32 v[178:179], v[122:123], v[144:145], v[138:139] op_sel_hi:[1,0,1]
	v_pk_fma_f32 v[180:181], v[120:121], v[144:145], v[136:137] op_sel_hi:[1,0,1]
	v_add_f32_e32 v172, 1.0, v172
	v_mul_f32_e32 v169, 0xbfb8aa3b, v174
	v_mul_f32_e32 v174, 0xbfb8aa3b, v180
	v_mul_f32_e32 v180, 0xbfb8aa3b, v181
	v_rcp_f32_e32 v181, v172
	v_mul_f32_e32 v172, 0xbfb8aa3b, v178
	v_exp_f32_e32 v172, v172
	v_mul_f32_e32 v175, 0xbfb8aa3b, v175
	v_exp_f32_e32 v169, v169
	v_exp_f32_e32 v174, v174
	v_add_f32_e32 v172, 1.0, v172
	v_rcp_f32_e32 v178, v172
	v_mul_f32_e32 v172, 0xbfb8aa3b, v173
	v_exp_f32_e32 v172, v172
	v_exp_f32_e32 v175, v175
	v_exp_f32_e32 v180, v180
	v_add_f32_e32 v169, 1.0, v169
	v_add_f32_e32 v172, 1.0, v172
	v_rcp_f32_e32 v173, v172
	v_mul_f32_e32 v172, 0xbfb8aa3b, v179
	v_exp_f32_e32 v172, v172
	v_add_f32_e32 v174, 1.0, v174
	v_add_f32_e32 v175, 1.0, v175
	v_add_f32_e32 v180, 1.0, v180
	v_add_f32_e32 v172, 1.0, v172
	v_rcp_f32_e32 v169, v169
	v_rcp_f32_e32 v174, v174
	v_rcp_f32_e32 v175, v175
	v_rcp_f32_e32 v180, v180
	v_rcp_f32_e32 v179, v172
	v_cvt_pk_bf16_f32 v173, v181, v173
	v_cvt_pk_bf16_f32 v172, v169, v175
	v_cvt_pk_bf16_f32 v174, v174, v180
	v_cvt_pk_bf16_f32 v175, v178, v179
	global_store_dwordx4 v[176:177], v[172:175], off
	v_pk_fma_f32 v[178:179], v[106:107], v[144:145], v[130:131] op_sel_hi:[1,0,1]
	v_pk_fma_f32 v[180:181], v[104:105], v[144:145], v[128:129] op_sel_hi:[1,0,1]
	v_pk_fma_f32 v[172:173], v[118:119], v[144:145], v[134:135] op_sel_hi:[1,0,1]
	v_mul_f32_e32 v169, 0xbfb8aa3b, v180
	v_mul_f32_e32 v172, 0xbfb8aa3b, v172
	v_exp_f32_e32 v172, v172
	v_pk_fma_f32 v[174:175], v[116:117], v[144:145], v[132:133] op_sel_hi:[1,0,1]
	v_exp_f32_e32 v169, v169
	v_mul_f32_e32 v144, 0xbfb8aa3b, v174
	v_add_f32_e32 v172, 1.0, v172
	v_rcp_f32_e32 v180, v172
	v_mul_f32_e32 v172, 0xbfb8aa3b, v178
	v_exp_f32_e32 v172, v172
	v_mul_f32_e32 v174, 0xbfb8aa3b, v175
	v_mul_f32_e32 v175, 0xbfb8aa3b, v181
	v_exp_f32_e32 v144, v144
	v_add_f32_e32 v172, 1.0, v172
	v_rcp_f32_e32 v178, v172
	v_mul_f32_e32 v172, 0xbfb8aa3b, v173
	v_exp_f32_e32 v172, v172
	v_exp_f32_e32 v174, v174
	v_exp_f32_e32 v175, v175
	v_add_f32_e32 v144, 1.0, v144
	v_add_f32_e32 v172, 1.0, v172
	v_rcp_f32_e32 v173, v172
	v_mul_f32_e32 v172, 0xbfb8aa3b, v179
	v_exp_f32_e32 v172, v172
	v_add_f32_e32 v169, 1.0, v169
	v_add_f32_e32 v174, 1.0, v174
	v_add_f32_e32 v175, 1.0, v175
	v_add_f32_e32 v172, 1.0, v172
	v_rcp_f32_e32 v144, v144
	v_rcp_f32_e32 v169, v169
	v_rcp_f32_e32 v174, v174
	v_rcp_f32_e32 v175, v175
	v_rcp_f32_e32 v179, v172
	v_cvt_pk_bf16_f32 v173, v180, v173
	v_cvt_pk_bf16_f32 v172, v144, v174
	v_cvt_pk_bf16_f32 v174, v169, v175
	v_cvt_pk_bf16_f32 v175, v178, v179
	global_store_dwordx4 v[176:177], v[172:175], off offset:256
	s_nop 1
	v_or_b32_e32 v172, 16, v168
	v_ashrrev_i32_e32 v173, 31, v172
	v_lshlrev_b64 v[174:175], 12, v[172:173]
	v_lshl_add_u64 v[174:175], s[60:61], 0, v[174:175]
	v_lshl_add_u64 v[172:173], v[172:173], 4, s[48:49]
	v_lshl_add_u64 v[176:177], v[174:175], 0, v[170:171]
	s_nop 1
	v_mov_b32_e32 v172, v210
	v_mov_b32_e32 v173, v211
	v_mov_b32_e32 v174, v212
	v_mov_b32_e32 v175, v213
	v_mov_b32_e32 v178, v173
	v_mov_b32_e32 v179, v174
	v_mov_b32_e32 v173, v175
	v_pk_add_f32 v[172:173], v[178:179], v[172:173]
	s_nop 0
	v_add_f32_e32 v144, v172, v173
	v_fmamk_f32 v144, v144, 0x3a800000, v184
	v_rsq_f32_e32 v144, v144
	s_nop 0
	v_pk_fma_f32 v[172:173], v[114:115], v[144:145], v[142:143] op_sel_hi:[1,0,1]
	s_nop 0
	v_mul_f32_e32 v172, 0xbfb8aa3b, v172
	v_exp_f32_e32 v172, v172
	v_pk_fma_f32 v[174:175], v[112:113], v[144:145], v[140:141] op_sel_hi:[1,0,1]
	v_pk_fma_f32 v[178:179], v[110:111], v[144:145], v[138:139] op_sel_hi:[1,0,1]
	v_pk_fma_f32 v[180:181], v[108:109], v[144:145], v[136:137] op_sel_hi:[1,0,1]
	v_add_f32_e32 v172, 1.0, v172
	v_mul_f32_e32 v169, 0xbfb8aa3b, v174
	v_mul_f32_e32 v174, 0xbfb8aa3b, v180
	v_mul_f32_e32 v180, 0xbfb8aa3b, v181
	v_rcp_f32_e32 v181, v172
	v_mul_f32_e32 v172, 0xbfb8aa3b, v178
	v_exp_f32_e32 v172, v172
	v_mul_f32_e32 v175, 0xbfb8aa3b, v175
	v_exp_f32_e32 v169, v169
	v_exp_f32_e32 v174, v174
	v_add_f32_e32 v172, 1.0, v172
	v_rcp_f32_e32 v178, v172
	v_mul_f32_e32 v172, 0xbfb8aa3b, v173
	v_exp_f32_e32 v172, v172
	v_exp_f32_e32 v175, v175
	v_exp_f32_e32 v180, v180
	v_add_f32_e32 v169, 1.0, v169
	v_add_f32_e32 v172, 1.0, v172
	v_rcp_f32_e32 v173, v172
	v_mul_f32_e32 v172, 0xbfb8aa3b, v179
	v_exp_f32_e32 v172, v172
	v_add_f32_e32 v174, 1.0, v174
	v_add_f32_e32 v175, 1.0, v175
	v_add_f32_e32 v180, 1.0, v180
	v_add_f32_e32 v172, 1.0, v172
	v_rcp_f32_e32 v169, v169
	v_rcp_f32_e32 v174, v174
	v_rcp_f32_e32 v175, v175
	v_rcp_f32_e32 v180, v180
	v_rcp_f32_e32 v179, v172
	v_cvt_pk_bf16_f32 v173, v181, v173
	v_cvt_pk_bf16_f32 v172, v169, v175
	v_cvt_pk_bf16_f32 v174, v174, v180
	v_cvt_pk_bf16_f32 v175, v178, v179
	global_store_dwordx4 v[176:177], v[172:175], off
	v_pk_fma_f32 v[178:179], v[90:91], v[144:145], v[130:131] op_sel_hi:[1,0,1]
	v_pk_fma_f32 v[180:181], v[88:89], v[144:145], v[128:129] op_sel_hi:[1,0,1]
	v_pk_fma_f32 v[172:173], v[98:99], v[144:145], v[134:135] op_sel_hi:[1,0,1]
	v_mul_f32_e32 v169, 0xbfb8aa3b, v180
	v_mul_f32_e32 v172, 0xbfb8aa3b, v172
	v_exp_f32_e32 v172, v172
	v_pk_fma_f32 v[174:175], v[96:97], v[144:145], v[132:133] op_sel_hi:[1,0,1]
	v_exp_f32_e32 v169, v169
	v_mul_f32_e32 v144, 0xbfb8aa3b, v174
	v_add_f32_e32 v172, 1.0, v172
	v_rcp_f32_e32 v180, v172
	v_mul_f32_e32 v172, 0xbfb8aa3b, v178
	v_exp_f32_e32 v172, v172
	v_mul_f32_e32 v174, 0xbfb8aa3b, v175
	v_mul_f32_e32 v175, 0xbfb8aa3b, v181
	v_exp_f32_e32 v144, v144
	v_add_f32_e32 v172, 1.0, v172
	v_rcp_f32_e32 v178, v172
	v_mul_f32_e32 v172, 0xbfb8aa3b, v173
	v_exp_f32_e32 v172, v172
	v_exp_f32_e32 v174, v174
	v_exp_f32_e32 v175, v175
	v_add_f32_e32 v144, 1.0, v144
	v_add_f32_e32 v172, 1.0, v172
	v_rcp_f32_e32 v173, v172
	v_mul_f32_e32 v172, 0xbfb8aa3b, v179
	v_exp_f32_e32 v172, v172
	v_add_f32_e32 v169, 1.0, v169
	v_add_f32_e32 v174, 1.0, v174
	v_add_f32_e32 v175, 1.0, v175
	v_add_f32_e32 v172, 1.0, v172
	v_rcp_f32_e32 v144, v144
	v_rcp_f32_e32 v169, v169
	v_rcp_f32_e32 v174, v174
	v_rcp_f32_e32 v175, v175
	v_rcp_f32_e32 v179, v172
	v_cvt_pk_bf16_f32 v173, v180, v173
	v_cvt_pk_bf16_f32 v172, v144, v174
	v_cvt_pk_bf16_f32 v174, v169, v175
	v_cvt_pk_bf16_f32 v175, v178, v179
	global_store_dwordx4 v[176:177], v[172:175], off offset:256
	s_nop 1
	v_or_b32_e32 v174, 32, v168
	v_ashrrev_i32_e32 v175, 31, v174
	v_lshlrev_b64 v[172:173], 12, v[174:175]
	v_lshl_add_u64 v[174:175], v[174:175], 4, s[48:49]
	s_nop 1
	v_mov_b32_e32 v174, v214
	v_mov_b32_e32 v175, v215
	v_mov_b32_e32 v176, v216
	v_mov_b32_e32 v177, v217
	v_lshl_add_u64 v[172:173], s[60:61], 0, v[172:173]
	v_lshl_add_u64 v[172:173], v[172:173], 0, v[170:171]
	v_mov_b32_e32 v178, v175
	v_mov_b32_e32 v179, v176
	v_mov_b32_e32 v175, v177
	v_pk_add_f32 v[174:175], v[178:179], v[174:175]
	s_nop 0
	v_add_f32_e32 v144, v174, v175
	v_fmamk_f32 v144, v144, 0x3a800000, v184
	v_rsq_f32_e32 v144, v144
	s_nop 0
	v_pk_fma_f32 v[174:175], v[102:103], v[144:145], v[142:143] op_sel_hi:[1,0,1]
	s_nop 0
	v_mul_f32_e32 v174, 0xbfb8aa3b, v174
	v_exp_f32_e32 v174, v174
	v_pk_fma_f32 v[176:177], v[100:101], v[144:145], v[140:141] op_sel_hi:[1,0,1]
	v_pk_fma_f32 v[178:179], v[94:95], v[144:145], v[138:139] op_sel_hi:[1,0,1]
	v_pk_fma_f32 v[180:181], v[92:93], v[144:145], v[136:137] op_sel_hi:[1,0,1]
	v_add_f32_e32 v174, 1.0, v174
	v_mul_f32_e32 v169, 0xbfb8aa3b, v176
	v_mul_f32_e32 v176, 0xbfb8aa3b, v180
	v_mul_f32_e32 v180, 0xbfb8aa3b, v181
	v_rcp_f32_e32 v181, v174
	v_mul_f32_e32 v174, 0xbfb8aa3b, v178
	v_exp_f32_e32 v174, v174
	v_mul_f32_e32 v177, 0xbfb8aa3b, v177
	v_exp_f32_e32 v169, v169
	v_exp_f32_e32 v176, v176
	v_add_f32_e32 v174, 1.0, v174
	v_rcp_f32_e32 v178, v174
	v_mul_f32_e32 v174, 0xbfb8aa3b, v175
	v_exp_f32_e32 v174, v174
	v_exp_f32_e32 v177, v177
	v_exp_f32_e32 v180, v180
	v_add_f32_e32 v169, 1.0, v169
	v_add_f32_e32 v174, 1.0, v174
	v_rcp_f32_e32 v175, v174
	v_mul_f32_e32 v174, 0xbfb8aa3b, v179
	v_exp_f32_e32 v174, v174
	v_add_f32_e32 v176, 1.0, v176
	v_add_f32_e32 v177, 1.0, v177
	v_add_f32_e32 v180, 1.0, v180
	v_add_f32_e32 v174, 1.0, v174
	v_rcp_f32_e32 v169, v169
	v_rcp_f32_e32 v176, v176
	v_rcp_f32_e32 v177, v177
	v_rcp_f32_e32 v180, v180
	v_rcp_f32_e32 v179, v174
	v_cvt_pk_bf16_f32 v175, v181, v175
	v_cvt_pk_bf16_f32 v174, v169, v177
	v_cvt_pk_bf16_f32 v176, v176, v180
	v_cvt_pk_bf16_f32 v177, v178, v179
	global_store_dwordx4 v[172:173], v[174:177], off
	v_pk_fma_f32 v[178:179], v[74:75], v[144:145], v[130:131] op_sel_hi:[1,0,1]
	v_pk_fma_f32 v[180:181], v[72:73], v[144:145], v[128:129] op_sel_hi:[1,0,1]
	v_pk_fma_f32 v[174:175], v[82:83], v[144:145], v[134:135] op_sel_hi:[1,0,1]
	v_mul_f32_e32 v169, 0xbfb8aa3b, v180
	v_mul_f32_e32 v174, 0xbfb8aa3b, v174
	v_exp_f32_e32 v174, v174
	v_pk_fma_f32 v[176:177], v[80:81], v[144:145], v[132:133] op_sel_hi:[1,0,1]
	v_exp_f32_e32 v169, v169
	v_mul_f32_e32 v144, 0xbfb8aa3b, v176
	v_add_f32_e32 v174, 1.0, v174
	v_rcp_f32_e32 v180, v174
	v_mul_f32_e32 v174, 0xbfb8aa3b, v178
	v_exp_f32_e32 v174, v174
	v_mul_f32_e32 v176, 0xbfb8aa3b, v177
	v_mul_f32_e32 v177, 0xbfb8aa3b, v181
	v_exp_f32_e32 v144, v144
	v_add_f32_e32 v174, 1.0, v174
	v_rcp_f32_e32 v178, v174
	v_mul_f32_e32 v174, 0xbfb8aa3b, v175
	v_exp_f32_e32 v174, v174
	v_exp_f32_e32 v176, v176
	v_exp_f32_e32 v177, v177
	v_add_f32_e32 v144, 1.0, v144
	v_add_f32_e32 v174, 1.0, v174
	v_rcp_f32_e32 v175, v174
	v_mul_f32_e32 v174, 0xbfb8aa3b, v179
	v_exp_f32_e32 v174, v174
	v_add_f32_e32 v169, 1.0, v169
	v_add_f32_e32 v176, 1.0, v176
	v_add_f32_e32 v177, 1.0, v177
	v_add_f32_e32 v174, 1.0, v174
	v_rcp_f32_e32 v144, v144
	v_rcp_f32_e32 v169, v169
	v_rcp_f32_e32 v176, v176
	v_rcp_f32_e32 v177, v177
	v_rcp_f32_e32 v179, v174
	v_cvt_pk_bf16_f32 v175, v180, v175
	v_cvt_pk_bf16_f32 v174, v144, v176
	v_cvt_pk_bf16_f32 v176, v169, v177
	v_cvt_pk_bf16_f32 v177, v178, v179
	global_store_dwordx4 v[172:173], v[174:177], off offset:256
	s_nop 1
	v_or_b32_e32 v174, 48, v168
	v_ashrrev_i32_e32 v175, 31, v174
	v_lshlrev_b64 v[172:173], 12, v[174:175]
	v_lshl_add_u64 v[174:175], v[174:175], 4, s[48:49]
	s_nop 1
	v_mov_b32_e32 v174, v218
	v_mov_b32_e32 v175, v219
	v_mov_b32_e32 v176, v220
	v_mov_b32_e32 v177, v221
	v_lshl_add_u64 v[172:173], s[60:61], 0, v[172:173]
	v_lshl_add_u64 v[172:173], v[172:173], 0, v[170:171]
	v_mov_b32_e32 v178, v175
	v_mov_b32_e32 v179, v176
	v_mov_b32_e32 v175, v177
	v_pk_add_f32 v[174:175], v[178:179], v[174:175]
	s_nop 0
	v_add_f32_e32 v144, v174, v175
	v_fmamk_f32 v144, v144, 0x3a800000, v184
	v_rsq_f32_e32 v144, v144
	s_nop 0
	v_pk_fma_f32 v[174:175], v[86:87], v[144:145], v[142:143] op_sel_hi:[1,0,1]
	s_nop 0
	v_mul_f32_e32 v174, 0xbfb8aa3b, v174
	v_exp_f32_e32 v174, v174
	v_pk_fma_f32 v[176:177], v[84:85], v[144:145], v[140:141] op_sel_hi:[1,0,1]
	v_pk_fma_f32 v[178:179], v[78:79], v[144:145], v[138:139] op_sel_hi:[1,0,1]
	v_pk_fma_f32 v[180:181], v[76:77], v[144:145], v[136:137] op_sel_hi:[1,0,1]
	v_add_f32_e32 v174, 1.0, v174
	v_mul_f32_e32 v169, 0xbfb8aa3b, v176
	v_mul_f32_e32 v176, 0xbfb8aa3b, v180
	v_mul_f32_e32 v180, 0xbfb8aa3b, v181
	v_rcp_f32_e32 v181, v174
	v_mul_f32_e32 v174, 0xbfb8aa3b, v178
	v_exp_f32_e32 v174, v174
	v_mul_f32_e32 v177, 0xbfb8aa3b, v177
	v_exp_f32_e32 v169, v169
	v_exp_f32_e32 v176, v176
	v_add_f32_e32 v174, 1.0, v174
	v_rcp_f32_e32 v178, v174
	v_mul_f32_e32 v174, 0xbfb8aa3b, v175
	v_exp_f32_e32 v174, v174
	v_exp_f32_e32 v177, v177
	v_exp_f32_e32 v180, v180
	v_add_f32_e32 v169, 1.0, v169
	v_add_f32_e32 v174, 1.0, v174
	v_rcp_f32_e32 v175, v174
	v_mul_f32_e32 v174, 0xbfb8aa3b, v179
	v_exp_f32_e32 v174, v174
	v_add_f32_e32 v176, 1.0, v176
	v_add_f32_e32 v177, 1.0, v177
	v_add_f32_e32 v180, 1.0, v180
	v_add_f32_e32 v174, 1.0, v174
	v_rcp_f32_e32 v169, v169
	v_rcp_f32_e32 v176, v176
	v_rcp_f32_e32 v177, v177
	v_rcp_f32_e32 v180, v180
	v_rcp_f32_e32 v179, v174
	v_cvt_pk_bf16_f32 v175, v181, v175
	v_cvt_pk_bf16_f32 v174, v169, v177
	v_cvt_pk_bf16_f32 v176, v176, v180
	v_cvt_pk_bf16_f32 v177, v178, v179
	global_store_dwordx4 v[172:173], v[174:177], off
	v_pk_fma_f32 v[178:179], v[66:67], v[144:145], v[130:131] op_sel_hi:[1,0,1]
	v_pk_fma_f32 v[180:181], v[64:65], v[144:145], v[128:129] op_sel_hi:[1,0,1]
	v_pk_fma_f32 v[174:175], v[70:71], v[144:145], v[134:135] op_sel_hi:[1,0,1]
	v_mul_f32_e32 v169, 0xbfb8aa3b, v180
	v_mul_f32_e32 v174, 0xbfb8aa3b, v174
	v_exp_f32_e32 v174, v174
	v_pk_fma_f32 v[176:177], v[68:69], v[144:145], v[132:133] op_sel_hi:[1,0,1]
	v_exp_f32_e32 v169, v169
	v_mul_f32_e32 v144, 0xbfb8aa3b, v176
	v_add_f32_e32 v174, 1.0, v174
	v_rcp_f32_e32 v180, v174
	v_mul_f32_e32 v174, 0xbfb8aa3b, v178
	v_exp_f32_e32 v174, v174
	v_mul_f32_e32 v176, 0xbfb8aa3b, v177
	v_mul_f32_e32 v177, 0xbfb8aa3b, v181
	v_exp_f32_e32 v144, v144
	v_add_f32_e32 v174, 1.0, v174
	v_rcp_f32_e32 v178, v174
	v_mul_f32_e32 v174, 0xbfb8aa3b, v175
	v_exp_f32_e32 v174, v174
	v_exp_f32_e32 v176, v176
	v_exp_f32_e32 v177, v177
	v_add_f32_e32 v144, 1.0, v144
	v_add_f32_e32 v174, 1.0, v174
	v_rcp_f32_e32 v175, v174
	v_mul_f32_e32 v174, 0xbfb8aa3b, v179
	v_exp_f32_e32 v174, v174
	v_add_f32_e32 v169, 1.0, v169
	v_add_f32_e32 v176, 1.0, v176
	v_add_f32_e32 v177, 1.0, v177
	v_add_f32_e32 v174, 1.0, v174
	v_rcp_f32_e32 v144, v144
	v_rcp_f32_e32 v169, v169
	v_rcp_f32_e32 v176, v176
	v_rcp_f32_e32 v177, v177
	v_rcp_f32_e32 v179, v174
	v_cvt_pk_bf16_f32 v175, v180, v175
	v_cvt_pk_bf16_f32 v174, v144, v176
	v_cvt_pk_bf16_f32 v176, v169, v177
	v_cvt_pk_bf16_f32 v177, v178, v179
	global_store_dwordx4 v[172:173], v[174:177], off offset:256
	s_nop 1
	v_add_u32_e32 v174, 0x80, v168
	v_ashrrev_i32_e32 v175, 31, v174
	v_lshlrev_b64 v[172:173], 12, v[174:175]
	v_lshl_add_u64 v[174:175], v[174:175], 4, s[48:49]
	s_nop 1
	v_mov_b32_e32 v174, v222
	v_mov_b32_e32 v175, v223
	v_mov_b32_e32 v176, v224
	v_mov_b32_e32 v177, v225
	v_lshl_add_u64 v[172:173], s[60:61], 0, v[172:173]
	v_lshl_add_u64 v[172:173], v[172:173], 0, v[170:171]
	v_mov_b32_e32 v178, v175
	v_mov_b32_e32 v179, v176
	v_mov_b32_e32 v175, v177
	v_pk_add_f32 v[174:175], v[178:179], v[174:175]
	s_nop 0
	v_add_f32_e32 v144, v174, v175
	v_fmamk_f32 v144, v144, 0x3a800000, v184
	v_rsq_f32_e32 v144, v144
	s_nop 0
	v_pk_fma_f32 v[174:175], v[62:63], v[144:145], v[142:143] op_sel_hi:[1,0,1]
	s_nop 0
	v_mul_f32_e32 v174, 0xbfb8aa3b, v174
	v_exp_f32_e32 v174, v174
	v_pk_fma_f32 v[176:177], v[60:61], v[144:145], v[140:141] op_sel_hi:[1,0,1]
	v_pk_fma_f32 v[178:179], v[58:59], v[144:145], v[138:139] op_sel_hi:[1,0,1]
	v_pk_fma_f32 v[180:181], v[56:57], v[144:145], v[136:137] op_sel_hi:[1,0,1]
	v_add_f32_e32 v174, 1.0, v174
	v_mul_f32_e32 v169, 0xbfb8aa3b, v176
	v_mul_f32_e32 v176, 0xbfb8aa3b, v180
	v_mul_f32_e32 v180, 0xbfb8aa3b, v181
	v_rcp_f32_e32 v181, v174
	v_mul_f32_e32 v174, 0xbfb8aa3b, v178
	v_exp_f32_e32 v174, v174
	v_mul_f32_e32 v177, 0xbfb8aa3b, v177
	v_exp_f32_e32 v169, v169
	v_exp_f32_e32 v176, v176
	v_add_f32_e32 v174, 1.0, v174
	v_rcp_f32_e32 v178, v174
	v_mul_f32_e32 v174, 0xbfb8aa3b, v175
	v_exp_f32_e32 v174, v174
	v_exp_f32_e32 v177, v177
	v_exp_f32_e32 v180, v180
	v_add_f32_e32 v169, 1.0, v169
	v_add_f32_e32 v174, 1.0, v174
	v_rcp_f32_e32 v175, v174
	v_mul_f32_e32 v174, 0xbfb8aa3b, v179
	v_exp_f32_e32 v174, v174
	v_add_f32_e32 v176, 1.0, v176
	v_add_f32_e32 v177, 1.0, v177
	v_add_f32_e32 v180, 1.0, v180
	v_add_f32_e32 v174, 1.0, v174
	v_rcp_f32_e32 v169, v169
	v_rcp_f32_e32 v176, v176
	v_rcp_f32_e32 v177, v177
	v_rcp_f32_e32 v180, v180
	v_rcp_f32_e32 v179, v174
	v_cvt_pk_bf16_f32 v175, v181, v175
	v_cvt_pk_bf16_f32 v174, v169, v177
	v_cvt_pk_bf16_f32 v176, v176, v180
	v_cvt_pk_bf16_f32 v177, v178, v179
	global_store_dwordx4 v[172:173], v[174:177], off
	v_pk_fma_f32 v[178:179], v[42:43], v[144:145], v[130:131] op_sel_hi:[1,0,1]
	v_pk_fma_f32 v[180:181], v[40:41], v[144:145], v[128:129] op_sel_hi:[1,0,1]
	v_pk_fma_f32 v[174:175], v[50:51], v[144:145], v[134:135] op_sel_hi:[1,0,1]
	v_mul_f32_e32 v169, 0xbfb8aa3b, v180
	v_mul_f32_e32 v174, 0xbfb8aa3b, v174
	v_exp_f32_e32 v174, v174
	v_pk_fma_f32 v[176:177], v[48:49], v[144:145], v[132:133] op_sel_hi:[1,0,1]
	v_exp_f32_e32 v169, v169
	v_mul_f32_e32 v144, 0xbfb8aa3b, v176
	v_add_f32_e32 v174, 1.0, v174
	v_rcp_f32_e32 v180, v174
	v_mul_f32_e32 v174, 0xbfb8aa3b, v178
	v_exp_f32_e32 v174, v174
	v_mul_f32_e32 v176, 0xbfb8aa3b, v177
	v_mul_f32_e32 v177, 0xbfb8aa3b, v181
	v_exp_f32_e32 v144, v144
	v_add_f32_e32 v174, 1.0, v174
	v_rcp_f32_e32 v178, v174
	v_mul_f32_e32 v174, 0xbfb8aa3b, v175
	v_exp_f32_e32 v174, v174
	v_exp_f32_e32 v176, v176
	v_exp_f32_e32 v177, v177
	v_add_f32_e32 v144, 1.0, v144
	v_add_f32_e32 v174, 1.0, v174
	v_rcp_f32_e32 v175, v174
	v_mul_f32_e32 v174, 0xbfb8aa3b, v179
	v_exp_f32_e32 v174, v174
	v_add_f32_e32 v169, 1.0, v169
	v_add_f32_e32 v176, 1.0, v176
	v_add_f32_e32 v177, 1.0, v177
	v_add_f32_e32 v174, 1.0, v174
	v_rcp_f32_e32 v144, v144
	v_rcp_f32_e32 v169, v169
	v_rcp_f32_e32 v176, v176
	v_rcp_f32_e32 v177, v177
	v_rcp_f32_e32 v179, v174
	v_cvt_pk_bf16_f32 v175, v180, v175
	v_cvt_pk_bf16_f32 v174, v144, v176
	v_cvt_pk_bf16_f32 v176, v169, v177
	v_cvt_pk_bf16_f32 v177, v178, v179
	global_store_dwordx4 v[172:173], v[174:177], off offset:256
	s_nop 1
	v_add_u32_e32 v174, 0x90, v168
	v_ashrrev_i32_e32 v175, 31, v174
	v_lshlrev_b64 v[172:173], 12, v[174:175]
	v_lshl_add_u64 v[174:175], v[174:175], 4, s[48:49]
	s_nop 1
	v_mov_b32_e32 v174, v226
	v_mov_b32_e32 v175, v227
	v_mov_b32_e32 v176, v228
	v_mov_b32_e32 v177, v229
	v_lshl_add_u64 v[172:173], s[60:61], 0, v[172:173]
	v_lshl_add_u64 v[172:173], v[172:173], 0, v[170:171]
	v_mov_b32_e32 v178, v175
	v_mov_b32_e32 v179, v176
	v_mov_b32_e32 v175, v177
	v_pk_add_f32 v[174:175], v[178:179], v[174:175]
	s_nop 0
	v_add_f32_e32 v144, v174, v175
	v_fmamk_f32 v144, v144, 0x3a800000, v184
	v_rsq_f32_e32 v144, v144
	s_nop 0
	v_pk_fma_f32 v[174:175], v[54:55], v[144:145], v[142:143] op_sel_hi:[1,0,1]
	s_nop 0
	v_mul_f32_e32 v174, 0xbfb8aa3b, v174
	v_exp_f32_e32 v174, v174
	v_pk_fma_f32 v[176:177], v[52:53], v[144:145], v[140:141] op_sel_hi:[1,0,1]
	v_pk_fma_f32 v[178:179], v[46:47], v[144:145], v[138:139] op_sel_hi:[1,0,1]
	v_pk_fma_f32 v[180:181], v[44:45], v[144:145], v[136:137] op_sel_hi:[1,0,1]
	v_add_f32_e32 v174, 1.0, v174
	v_mul_f32_e32 v169, 0xbfb8aa3b, v176
	v_mul_f32_e32 v176, 0xbfb8aa3b, v180
	v_mul_f32_e32 v180, 0xbfb8aa3b, v181
	v_rcp_f32_e32 v181, v174
	v_mul_f32_e32 v174, 0xbfb8aa3b, v178
	v_exp_f32_e32 v174, v174
	v_mul_f32_e32 v177, 0xbfb8aa3b, v177
	v_exp_f32_e32 v169, v169
	v_exp_f32_e32 v176, v176
	v_add_f32_e32 v174, 1.0, v174
	v_rcp_f32_e32 v178, v174
	v_mul_f32_e32 v174, 0xbfb8aa3b, v175
	v_exp_f32_e32 v174, v174
	v_exp_f32_e32 v177, v177
	v_exp_f32_e32 v180, v180
	v_add_f32_e32 v169, 1.0, v169
	v_add_f32_e32 v174, 1.0, v174
	v_rcp_f32_e32 v175, v174
	v_mul_f32_e32 v174, 0xbfb8aa3b, v179
	v_exp_f32_e32 v174, v174
	v_add_f32_e32 v176, 1.0, v176
	v_add_f32_e32 v177, 1.0, v177
	v_add_f32_e32 v180, 1.0, v180
	v_add_f32_e32 v174, 1.0, v174
	v_rcp_f32_e32 v169, v169
	v_rcp_f32_e32 v176, v176
	v_rcp_f32_e32 v177, v177
	v_rcp_f32_e32 v180, v180
	v_rcp_f32_e32 v179, v174
	v_cvt_pk_bf16_f32 v175, v181, v175
	v_cvt_pk_bf16_f32 v174, v169, v177
	v_cvt_pk_bf16_f32 v176, v176, v180
	v_cvt_pk_bf16_f32 v177, v178, v179
	global_store_dwordx4 v[172:173], v[174:177], off
	v_pk_fma_f32 v[178:179], v[26:27], v[144:145], v[130:131] op_sel_hi:[1,0,1]
	v_pk_fma_f32 v[180:181], v[24:25], v[144:145], v[128:129] op_sel_hi:[1,0,1]
	v_pk_fma_f32 v[174:175], v[34:35], v[144:145], v[134:135] op_sel_hi:[1,0,1]
	v_mul_f32_e32 v169, 0xbfb8aa3b, v180
	v_mul_f32_e32 v174, 0xbfb8aa3b, v174
	v_exp_f32_e32 v174, v174
	v_pk_fma_f32 v[176:177], v[32:33], v[144:145], v[132:133] op_sel_hi:[1,0,1]
	v_exp_f32_e32 v169, v169
	v_mul_f32_e32 v144, 0xbfb8aa3b, v176
	v_add_f32_e32 v174, 1.0, v174
	v_rcp_f32_e32 v180, v174
	v_mul_f32_e32 v174, 0xbfb8aa3b, v178
	v_exp_f32_e32 v174, v174
	v_mul_f32_e32 v176, 0xbfb8aa3b, v177
	v_mul_f32_e32 v177, 0xbfb8aa3b, v181
	v_exp_f32_e32 v144, v144
	v_add_f32_e32 v174, 1.0, v174
	v_rcp_f32_e32 v178, v174
	v_mul_f32_e32 v174, 0xbfb8aa3b, v175
	v_exp_f32_e32 v174, v174
	v_exp_f32_e32 v176, v176
	v_exp_f32_e32 v177, v177
	v_add_f32_e32 v144, 1.0, v144
	v_add_f32_e32 v174, 1.0, v174
	v_rcp_f32_e32 v175, v174
	v_mul_f32_e32 v174, 0xbfb8aa3b, v179
	v_exp_f32_e32 v174, v174
	v_add_f32_e32 v169, 1.0, v169
	v_add_f32_e32 v176, 1.0, v176
	v_add_f32_e32 v177, 1.0, v177
	v_add_f32_e32 v174, 1.0, v174
	v_rcp_f32_e32 v144, v144
	v_rcp_f32_e32 v169, v169
	v_rcp_f32_e32 v176, v176
	v_rcp_f32_e32 v177, v177
	v_rcp_f32_e32 v179, v174
	v_cvt_pk_bf16_f32 v175, v180, v175
	v_cvt_pk_bf16_f32 v174, v144, v176
	v_cvt_pk_bf16_f32 v176, v169, v177
	v_cvt_pk_bf16_f32 v177, v178, v179
	global_store_dwordx4 v[172:173], v[174:177], off offset:256
	s_nop 1
	v_add_u32_e32 v174, 0xa0, v168
	v_ashrrev_i32_e32 v175, 31, v174
	v_lshlrev_b64 v[172:173], 12, v[174:175]
	v_lshl_add_u64 v[174:175], v[174:175], 4, s[48:49]
	s_nop 1
	v_mov_b32_e32 v174, v230
	v_mov_b32_e32 v175, v231
	v_mov_b32_e32 v176, v232
	v_mov_b32_e32 v177, v233
	v_lshl_add_u64 v[172:173], s[60:61], 0, v[172:173]
	v_lshl_add_u64 v[172:173], v[172:173], 0, v[170:171]
	v_mov_b32_e32 v178, v175
	v_mov_b32_e32 v179, v176
	v_mov_b32_e32 v175, v177
	v_pk_add_f32 v[174:175], v[178:179], v[174:175]
	s_nop 0
	v_add_f32_e32 v144, v174, v175
	v_fmamk_f32 v144, v144, 0x3a800000, v184
	v_rsq_f32_e32 v144, v144
	s_nop 0
	v_pk_fma_f32 v[174:175], v[38:39], v[144:145], v[142:143] op_sel_hi:[1,0,1]
	s_nop 0
	v_mul_f32_e32 v174, 0xbfb8aa3b, v174
	v_exp_f32_e32 v174, v174
	v_pk_fma_f32 v[176:177], v[36:37], v[144:145], v[140:141] op_sel_hi:[1,0,1]
	v_pk_fma_f32 v[178:179], v[30:31], v[144:145], v[138:139] op_sel_hi:[1,0,1]
	v_pk_fma_f32 v[180:181], v[28:29], v[144:145], v[136:137] op_sel_hi:[1,0,1]
	v_add_f32_e32 v174, 1.0, v174
	v_mul_f32_e32 v169, 0xbfb8aa3b, v176
	v_mul_f32_e32 v176, 0xbfb8aa3b, v180
	v_mul_f32_e32 v180, 0xbfb8aa3b, v181
	v_rcp_f32_e32 v181, v174
	v_mul_f32_e32 v174, 0xbfb8aa3b, v178
	v_exp_f32_e32 v174, v174
	v_mul_f32_e32 v177, 0xbfb8aa3b, v177
	v_exp_f32_e32 v169, v169
	v_exp_f32_e32 v176, v176
	v_add_f32_e32 v174, 1.0, v174
	v_rcp_f32_e32 v178, v174
	v_mul_f32_e32 v174, 0xbfb8aa3b, v175
	v_exp_f32_e32 v174, v174
	v_exp_f32_e32 v177, v177
	v_exp_f32_e32 v180, v180
	v_add_f32_e32 v169, 1.0, v169
	v_add_f32_e32 v174, 1.0, v174
	v_rcp_f32_e32 v175, v174
	v_mul_f32_e32 v174, 0xbfb8aa3b, v179
	v_exp_f32_e32 v174, v174
	v_add_f32_e32 v176, 1.0, v176
	v_add_f32_e32 v177, 1.0, v177
	v_add_f32_e32 v180, 1.0, v180
	v_add_f32_e32 v174, 1.0, v174
	v_rcp_f32_e32 v169, v169
	v_rcp_f32_e32 v176, v176
	v_rcp_f32_e32 v177, v177
	v_rcp_f32_e32 v180, v180
	v_rcp_f32_e32 v179, v174
	v_cvt_pk_bf16_f32 v175, v181, v175
	v_cvt_pk_bf16_f32 v174, v169, v177
	v_cvt_pk_bf16_f32 v176, v176, v180
	v_cvt_pk_bf16_f32 v177, v178, v179
	global_store_dwordx4 v[172:173], v[174:177], off
	v_pk_fma_f32 v[178:179], v[10:11], v[144:145], v[130:131] op_sel_hi:[1,0,1]
	v_pk_fma_f32 v[180:181], v[8:9], v[144:145], v[128:129] op_sel_hi:[1,0,1]
	v_pk_fma_f32 v[174:175], v[18:19], v[144:145], v[134:135] op_sel_hi:[1,0,1]
	v_mul_f32_e32 v169, 0xbfb8aa3b, v180
	v_mul_f32_e32 v174, 0xbfb8aa3b, v174
	v_exp_f32_e32 v174, v174
	v_pk_fma_f32 v[176:177], v[16:17], v[144:145], v[132:133] op_sel_hi:[1,0,1]
	v_exp_f32_e32 v169, v169
	v_mul_f32_e32 v144, 0xbfb8aa3b, v176
	v_add_f32_e32 v174, 1.0, v174
	v_rcp_f32_e32 v180, v174
	v_mul_f32_e32 v174, 0xbfb8aa3b, v178
	v_exp_f32_e32 v174, v174
	v_mul_f32_e32 v176, 0xbfb8aa3b, v177
	v_mul_f32_e32 v177, 0xbfb8aa3b, v181
	v_exp_f32_e32 v144, v144
	v_add_f32_e32 v174, 1.0, v174
	v_rcp_f32_e32 v178, v174
	v_mul_f32_e32 v174, 0xbfb8aa3b, v175
	v_exp_f32_e32 v174, v174
	v_exp_f32_e32 v176, v176
	v_exp_f32_e32 v177, v177
	v_add_f32_e32 v144, 1.0, v144
	v_add_f32_e32 v174, 1.0, v174
	v_rcp_f32_e32 v175, v174
	v_mul_f32_e32 v174, 0xbfb8aa3b, v179
	v_exp_f32_e32 v174, v174
	v_add_f32_e32 v169, 1.0, v169
	v_add_f32_e32 v176, 1.0, v176
	v_add_f32_e32 v177, 1.0, v177
	v_add_f32_e32 v174, 1.0, v174
	v_rcp_f32_e32 v144, v144
	v_rcp_f32_e32 v169, v169
	v_rcp_f32_e32 v176, v176
	v_rcp_f32_e32 v177, v177
	v_rcp_f32_e32 v179, v174
	v_cvt_pk_bf16_f32 v175, v180, v175
	v_cvt_pk_bf16_f32 v174, v144, v176
	v_cvt_pk_bf16_f32 v176, v169, v177
	v_cvt_pk_bf16_f32 v177, v178, v179
	global_store_dwordx4 v[172:173], v[174:177], off offset:256
	v_add_u32_e32 v172, 0xb0, v168
	v_ashrrev_i32_e32 v173, 31, v172
	v_lshlrev_b64 v[174:175], 12, v[172:173]
	v_lshl_add_u64 v[174:175], s[60:61], 0, v[174:175]
	v_lshl_add_u64 v[172:173], v[172:173], 4, s[48:49]
	v_lshl_add_u64 v[170:171], v[174:175], 0, v[170:171]
	s_nop 1
	v_mov_b32_e32 v172, v234
	v_mov_b32_e32 v173, v235
	v_mov_b32_e32 v174, v236
	v_mov_b32_e32 v175, v237
	v_mov_b32_e32 v176, v173
	v_mov_b32_e32 v177, v174
	v_mov_b32_e32 v173, v175
	v_pk_add_f32 v[172:173], v[176:177], v[172:173]
	s_nop 0
	v_add_f32_e32 v144, v172, v173
	v_fmamk_f32 v144, v144, 0x3a800000, v184
	v_rsq_f32_e32 v144, v144
	s_nop 0
	v_pk_fma_f32 v[138:139], v[14:15], v[144:145], v[138:139] op_sel_hi:[1,0,1]
	v_pk_fma_f32 v[136:137], v[12:13], v[144:145], v[136:137] op_sel_hi:[1,0,1]
	v_mul_f32_e32 v138, 0xbfb8aa3b, v138
	v_mul_f32_e32 v136, 0xbfb8aa3b, v136
	v_mul_f32_e32 v137, 0xbfb8aa3b, v137
	v_exp_f32_e32 v136, v136
	v_exp_f32_e32 v137, v137
	v_exp_f32_e32 v138, v138
	v_pk_fma_f32 v[142:143], v[22:23], v[144:145], v[142:143] op_sel_hi:[1,0,1]
	v_pk_fma_f32 v[140:141], v[20:21], v[144:145], v[140:141] op_sel_hi:[1,0,1]
	v_add_f32_e32 v136, 1.0, v136
	v_add_f32_e32 v137, 1.0, v137
	v_add_f32_e32 v138, 1.0, v138
	v_mul_f32_e32 v140, 0xbfb8aa3b, v140
	v_rcp_f32_e32 v169, v136
	v_mul_f32_e32 v136, 0xbfb8aa3b, v141
	v_rcp_f32_e32 v141, v137
	v_mul_f32_e32 v137, 0xbfb8aa3b, v142
	v_rcp_f32_e32 v142, v138
	v_mul_f32_e32 v138, 0xbfb8aa3b, v143
	v_mul_f32_e32 v139, 0xbfb8aa3b, v139
	v_exp_f32_e32 v140, v140
	v_exp_f32_e32 v136, v136
	v_exp_f32_e32 v137, v137
	v_exp_f32_e32 v138, v138
	v_exp_f32_e32 v139, v139
	v_pk_fma_f32 v[130:131], v[2:3], v[144:145], v[130:131] op_sel_hi:[1,0,1]
	v_pk_fma_f32 v[128:129], v[0:1], v[144:145], v[128:129] op_sel_hi:[1,0,1]
	v_add_f32_e32 v140, 1.0, v140
	v_add_f32_e32 v136, 1.0, v136
	v_add_f32_e32 v137, 1.0, v137
	v_add_f32_e32 v138, 1.0, v138
	v_add_f32_e32 v139, 1.0, v139
	v_mul_f32_e32 v128, 0xbfb8aa3b, v128
	v_mul_f32_e32 v129, 0xbfb8aa3b, v129
	v_mul_f32_e32 v130, 0xbfb8aa3b, v130
	v_rcp_f32_e32 v140, v140
	v_rcp_f32_e32 v136, v136
	v_rcp_f32_e32 v137, v137
	v_rcp_f32_e32 v138, v138
	v_rcp_f32_e32 v139, v139
	v_exp_f32_e32 v128, v128
	v_exp_f32_e32 v129, v129
	v_exp_f32_e32 v130, v130
	v_cvt_pk_bf16_f32 v136, v140, v136
	v_cvt_pk_bf16_f32 v137, v137, v138
	v_cvt_pk_bf16_f32 v138, v169, v141
	v_cvt_pk_bf16_f32 v139, v142, v139
	v_pk_fma_f32 v[134:135], v[6:7], v[144:145], v[134:135] op_sel_hi:[1,0,1]
	v_pk_fma_f32 v[132:133], v[4:5], v[144:145], v[132:133] op_sel_hi:[1,0,1]
	v_add_f32_e32 v128, 1.0, v128
	v_add_f32_e32 v129, 1.0, v129
	v_add_f32_e32 v130, 1.0, v130
	global_store_dwordx4 v[170:171], v[136:139], off
	v_mul_f32_e32 v132, 0xbfb8aa3b, v132
	v_mul_f32_e32 v131, 0xbfb8aa3b, v131
	v_rcp_f32_e32 v136, v128
	v_mul_f32_e32 v128, 0xbfb8aa3b, v133
	v_rcp_f32_e32 v133, v129
	v_mul_f32_e32 v129, 0xbfb8aa3b, v134
	v_rcp_f32_e32 v134, v130
	v_mul_f32_e32 v130, 0xbfb8aa3b, v135
	v_exp_f32_e32 v132, v132
	v_exp_f32_e32 v128, v128
	v_exp_f32_e32 v129, v129
	v_exp_f32_e32 v130, v130
	v_exp_f32_e32 v131, v131
	v_add_f32_e32 v132, 1.0, v132
	v_add_f32_e32 v128, 1.0, v128
	v_add_f32_e32 v129, 1.0, v129
	v_add_f32_e32 v130, 1.0, v130
	v_add_f32_e32 v131, 1.0, v131
	v_rcp_f32_e32 v132, v132
	v_rcp_f32_e32 v128, v128
	v_rcp_f32_e32 v129, v129
	v_rcp_f32_e32 v130, v130
	v_rcp_f32_e32 v131, v131
	v_cvt_pk_bf16_f32 v128, v132, v128
	v_cvt_pk_bf16_f32 v129, v129, v130
	v_cvt_pk_bf16_f32 v130, v136, v133
	v_cvt_pk_bf16_f32 v131, v134, v131
	global_store_dwordx4 v[170:171], v[128:131], off offset:256

.LBB0_626:
	v_ashrrev_i32_e32 v169, 31, v168
	v_lshl_add_u64 v[128:129], v[168:169], 4, s[48:49]
	global_load_dwordx4 v[210:213], v[128:129], off offset:256
	global_load_dwordx4 v[214:217], v[128:129], off offset:512
	global_load_dwordx4 v[218:221], v[128:129], off offset:768
	global_load_dwordx4 v[222:225], v[128:129], off offset:2048
	global_load_dwordx4 v[226:229], v[128:129], off offset:2304
	global_load_dwordx4 v[230:233], v[128:129], off offset:2560
	global_load_dwordx4 v[234:237], v[128:129], off offset:2816
	global_load_dwordx4 v[130:133], v[128:129], off
	s_and_b32 s2, s68, -2
	s_cmp_eq_u32 s2, 2
	s_cselect_b64 vcc, -1, 0
	v_lshlrev_b32_e32 v144, 1, v162
	v_lshl_add_u64 v[128:129], s[0:1], 0, v[144:145]
	v_lshlrev_b64 v[134:135], 10, v[168:169]
	v_or_b32_e32 v140, 16, v168
	v_lshl_add_u64 v[142:143], v[128:129], 0, v[134:135]
	v_ashrrev_i32_e32 v141, 31, v140
	v_lshl_add_u64 v[170:171], v[140:141], 4, s[48:49]
	s_waitcnt vmcnt(0)
	v_mov_b32_e32 v136, v131
	v_mov_b32_e32 v137, v132
	v_mov_b32_e32 v131, v133
	v_pk_add_f32 v[130:131], v[136:137], v[130:131]
	s_nop 0
	v_add_f32_e32 v130, v130, v131
	v_fmamk_f32 v130, v130, 0x3a800000, v184
	v_rsq_f32_e32 v131, v130
	v_mov_b32_e32 v130, 0x3e38aa3b
	v_cndmask_b32_e32 v130, 1.0, v130, vcc
	v_mul_f32_e32 v132, v130, v131
	v_pk_mul_f32 v[134:135], v[126:127], v[132:133] op_sel_hi:[1,0]
	v_pk_mul_f32 v[136:137], v[124:125], v[132:133] op_sel_hi:[1,0]
	v_pk_mul_f32 v[138:139], v[122:123], v[132:133] op_sel_hi:[1,0]
	v_pk_mul_f32 v[172:173], v[120:121], v[132:133] op_sel_hi:[1,0]
	v_pk_mul_f32 v[174:175], v[118:119], v[132:133] op_sel_hi:[1,0]
	v_pk_mul_f32 v[176:177], v[116:117], v[132:133] op_sel_hi:[1,0]
	v_pk_mul_f32 v[178:179], v[106:107], v[132:133] op_sel_hi:[1,0]
	v_pk_mul_f32 v[180:181], v[104:105], v[132:133] op_sel_hi:[1,0]
	v_cvt_pk_bf16_f32 v132, v136, v137
	v_cvt_pk_bf16_f32 v133, v134, v135
	v_cvt_pk_bf16_f32 v134, v172, v173
	v_cvt_pk_bf16_f32 v135, v138, v139
	v_cvt_pk_bf16_f32 v136, v176, v177
	v_cvt_pk_bf16_f32 v137, v174, v175
	v_cvt_pk_bf16_f32 v138, v180, v181
	v_cvt_pk_bf16_f32 v139, v178, v179
	global_store_dwordx4 v[142:143], v[132:135], off
	global_store_dwordx4 v[142:143], v[136:139], off offset:256
	s_nop 1
	v_mov_b32_e32 v132, v210
	v_mov_b32_e32 v133, v211
	v_mov_b32_e32 v134, v212
	v_mov_b32_e32 v135, v213
	v_or_b32_e32 v142, 32, v168
	v_ashrrev_i32_e32 v143, 31, v142
	v_mov_b32_e32 v136, v133
	v_mov_b32_e32 v137, v134
	v_mov_b32_e32 v133, v135
	v_pk_add_f32 v[132:133], v[136:137], v[132:133]
	s_nop 0
	v_add_f32_e32 v131, v132, v133
	v_fmamk_f32 v131, v131, 0x3a800000, v184
	v_rsq_f32_e32 v131, v131
	v_lshlrev_b64 v[132:133], 10, v[140:141]
	v_lshl_add_u64 v[170:171], v[128:129], 0, v[132:133]
	v_lshl_add_u64 v[140:141], v[142:143], 4, s[48:49]
	v_mul_f32_e32 v132, v130, v131
	v_pk_mul_f32 v[134:135], v[114:115], v[132:133] op_sel_hi:[1,0]
	v_pk_mul_f32 v[136:137], v[112:113], v[132:133] op_sel_hi:[1,0]
	v_pk_mul_f32 v[138:139], v[110:111], v[132:133] op_sel_hi:[1,0]
	v_pk_mul_f32 v[172:173], v[108:109], v[132:133] op_sel_hi:[1,0]
	v_pk_mul_f32 v[174:175], v[98:99], v[132:133] op_sel_hi:[1,0]
	v_pk_mul_f32 v[176:177], v[96:97], v[132:133] op_sel_hi:[1,0]
	v_pk_mul_f32 v[178:179], v[90:91], v[132:133] op_sel_hi:[1,0]
	v_pk_mul_f32 v[180:181], v[88:89], v[132:133] op_sel_hi:[1,0]
	v_cvt_pk_bf16_f32 v132, v136, v137
	v_cvt_pk_bf16_f32 v133, v134, v135
	v_cvt_pk_bf16_f32 v134, v172, v173
	v_cvt_pk_bf16_f32 v135, v138, v139
	v_cvt_pk_bf16_f32 v136, v176, v177
	v_cvt_pk_bf16_f32 v137, v174, v175
	v_cvt_pk_bf16_f32 v138, v180, v181
	v_cvt_pk_bf16_f32 v139, v178, v179
	global_store_dwordx4 v[170:171], v[132:135], off
	global_store_dwordx4 v[170:171], v[136:139], off offset:256
	s_nop 1
	v_mov_b32_e32 v132, v214
	v_mov_b32_e32 v133, v215
	v_mov_b32_e32 v134, v216
	v_mov_b32_e32 v135, v217
	v_or_b32_e32 v140, 48, v168
	v_ashrrev_i32_e32 v141, 31, v140
	v_mov_b32_e32 v136, v133
	v_mov_b32_e32 v137, v134
	v_mov_b32_e32 v133, v135
	v_pk_add_f32 v[132:133], v[136:137], v[132:133]
	s_nop 0
	v_add_f32_e32 v131, v132, v133
	v_fmamk_f32 v131, v131, 0x3a800000, v184
	v_rsq_f32_e32 v131, v131
	v_lshlrev_b64 v[132:133], 10, v[142:143]
	v_lshl_add_u64 v[170:171], v[128:129], 0, v[132:133]
	v_lshl_add_u64 v[142:143], v[140:141], 4, s[48:49]
	v_mul_f32_e32 v132, v130, v131
	v_pk_mul_f32 v[134:135], v[102:103], v[132:133] op_sel_hi:[1,0]
	v_pk_mul_f32 v[136:137], v[100:101], v[132:133] op_sel_hi:[1,0]
	v_pk_mul_f32 v[138:139], v[94:95], v[132:133] op_sel_hi:[1,0]
	v_pk_mul_f32 v[172:173], v[92:93], v[132:133] op_sel_hi:[1,0]
	v_pk_mul_f32 v[174:175], v[82:83], v[132:133] op_sel_hi:[1,0]
	v_pk_mul_f32 v[176:177], v[80:81], v[132:133] op_sel_hi:[1,0]
	v_pk_mul_f32 v[178:179], v[74:75], v[132:133] op_sel_hi:[1,0]
	v_pk_mul_f32 v[180:181], v[72:73], v[132:133] op_sel_hi:[1,0]
	v_cvt_pk_bf16_f32 v132, v136, v137
	v_cvt_pk_bf16_f32 v133, v134, v135
	v_cvt_pk_bf16_f32 v134, v172, v173
	v_cvt_pk_bf16_f32 v135, v138, v139
	v_cvt_pk_bf16_f32 v136, v176, v177
	v_cvt_pk_bf16_f32 v137, v174, v175
	v_cvt_pk_bf16_f32 v138, v180, v181
	v_cvt_pk_bf16_f32 v139, v178, v179
	global_store_dwordx4 v[170:171], v[132:135], off
	global_store_dwordx4 v[170:171], v[136:139], off offset:256
	s_nop 1
	v_mov_b32_e32 v132, v218
	v_mov_b32_e32 v133, v219
	v_mov_b32_e32 v134, v220
	v_mov_b32_e32 v135, v221
	v_add_u32_e32 v142, 0x80, v168
	v_ashrrev_i32_e32 v143, 31, v142
	v_mov_b32_e32 v136, v133
	v_mov_b32_e32 v137, v134
	v_mov_b32_e32 v133, v135
	v_pk_add_f32 v[132:133], v[136:137], v[132:133]
	s_nop 0
	v_add_f32_e32 v131, v132, v133
	v_fmamk_f32 v131, v131, 0x3a800000, v184
	v_rsq_f32_e32 v131, v131
	v_lshlrev_b64 v[132:133], 10, v[140:141]
	v_lshl_add_u64 v[170:171], v[128:129], 0, v[132:133]
	v_lshl_add_u64 v[140:141], v[142:143], 4, s[48:49]
	v_mul_f32_e32 v132, v130, v131
	v_pk_mul_f32 v[134:135], v[86:87], v[132:133] op_sel_hi:[1,0]
	v_pk_mul_f32 v[136:137], v[84:85], v[132:133] op_sel_hi:[1,0]
	v_pk_mul_f32 v[138:139], v[78:79], v[132:133] op_sel_hi:[1,0]
	v_pk_mul_f32 v[172:173], v[76:77], v[132:133] op_sel_hi:[1,0]
	v_pk_mul_f32 v[174:175], v[70:71], v[132:133] op_sel_hi:[1,0]
	v_pk_mul_f32 v[176:177], v[68:69], v[132:133] op_sel_hi:[1,0]
	v_pk_mul_f32 v[178:179], v[66:67], v[132:133] op_sel_hi:[1,0]
	v_pk_mul_f32 v[180:181], v[64:65], v[132:133] op_sel_hi:[1,0]
	v_cvt_pk_bf16_f32 v132, v136, v137
	v_cvt_pk_bf16_f32 v133, v134, v135
	v_cvt_pk_bf16_f32 v134, v172, v173
	v_cvt_pk_bf16_f32 v135, v138, v139
	v_cvt_pk_bf16_f32 v136, v176, v177
	v_cvt_pk_bf16_f32 v137, v174, v175
	v_cvt_pk_bf16_f32 v138, v180, v181
	v_cvt_pk_bf16_f32 v139, v178, v179
	global_store_dwordx4 v[170:171], v[132:135], off
	global_store_dwordx4 v[170:171], v[136:139], off offset:256
	s_nop 1
	v_mov_b32_e32 v132, v222
	v_mov_b32_e32 v133, v223
	v_mov_b32_e32 v134, v224
	v_mov_b32_e32 v135, v225
	v_add_u32_e32 v140, 0x90, v168
	v_ashrrev_i32_e32 v141, 31, v140
	v_mov_b32_e32 v136, v133
	v_mov_b32_e32 v137, v134
	v_mov_b32_e32 v133, v135
	v_pk_add_f32 v[132:133], v[136:137], v[132:133]
	s_nop 0
	v_add_f32_e32 v131, v132, v133
	v_fmamk_f32 v131, v131, 0x3a800000, v184
	v_rsq_f32_e32 v131, v131
	v_lshlrev_b64 v[132:133], 10, v[142:143]
	v_lshl_add_u64 v[170:171], v[128:129], 0, v[132:133]
	v_lshl_add_u64 v[142:143], v[140:141], 4, s[48:49]
	v_mul_f32_e32 v132, v130, v131
	v_pk_mul_f32 v[134:135], v[62:63], v[132:133] op_sel_hi:[1,0]
	v_pk_mul_f32 v[136:137], v[60:61], v[132:133] op_sel_hi:[1,0]
	v_pk_mul_f32 v[138:139], v[58:59], v[132:133] op_sel_hi:[1,0]
	v_pk_mul_f32 v[172:173], v[56:57], v[132:133] op_sel_hi:[1,0]
	v_pk_mul_f32 v[174:175], v[50:51], v[132:133] op_sel_hi:[1,0]
	v_pk_mul_f32 v[176:177], v[48:49], v[132:133] op_sel_hi:[1,0]
	v_pk_mul_f32 v[178:179], v[42:43], v[132:133] op_sel_hi:[1,0]
	v_pk_mul_f32 v[180:181], v[40:41], v[132:133] op_sel_hi:[1,0]
	v_cvt_pk_bf16_f32 v132, v136, v137
	v_cvt_pk_bf16_f32 v133, v134, v135
	v_cvt_pk_bf16_f32 v134, v172, v173
	v_cvt_pk_bf16_f32 v135, v138, v139
	v_cvt_pk_bf16_f32 v136, v176, v177
	v_cvt_pk_bf16_f32 v137, v174, v175
	v_cvt_pk_bf16_f32 v138, v180, v181
	v_cvt_pk_bf16_f32 v139, v178, v179
	global_store_dwordx4 v[170:171], v[132:135], off
	global_store_dwordx4 v[170:171], v[136:139], off offset:256
	s_nop 1
	v_mov_b32_e32 v132, v226
	v_mov_b32_e32 v133, v227
	v_mov_b32_e32 v134, v228
	v_mov_b32_e32 v135, v229
	v_add_u32_e32 v142, 0xa0, v168
	v_ashrrev_i32_e32 v143, 31, v142
	v_mov_b32_e32 v136, v133
	v_mov_b32_e32 v137, v134
	v_mov_b32_e32 v133, v135
	v_pk_add_f32 v[132:133], v[136:137], v[132:133]
	s_nop 0
	v_add_f32_e32 v131, v132, v133
	v_fmamk_f32 v131, v131, 0x3a800000, v184
	v_rsq_f32_e32 v131, v131
	v_lshlrev_b64 v[132:133], 10, v[140:141]
	v_lshl_add_u64 v[170:171], v[128:129], 0, v[132:133]
	v_lshl_add_u64 v[140:141], v[142:143], 4, s[48:49]
	v_mul_f32_e32 v132, v130, v131
	v_pk_mul_f32 v[134:135], v[54:55], v[132:133] op_sel_hi:[1,0]
	v_pk_mul_f32 v[136:137], v[52:53], v[132:133] op_sel_hi:[1,0]
	v_pk_mul_f32 v[138:139], v[46:47], v[132:133] op_sel_hi:[1,0]
	v_pk_mul_f32 v[172:173], v[44:45], v[132:133] op_sel_hi:[1,0]
	v_pk_mul_f32 v[174:175], v[34:35], v[132:133] op_sel_hi:[1,0]
	v_pk_mul_f32 v[176:177], v[32:33], v[132:133] op_sel_hi:[1,0]
	v_pk_mul_f32 v[178:179], v[26:27], v[132:133] op_sel_hi:[1,0]
	v_pk_mul_f32 v[180:181], v[24:25], v[132:133] op_sel_hi:[1,0]
	v_cvt_pk_bf16_f32 v132, v136, v137
	v_cvt_pk_bf16_f32 v133, v134, v135
	v_cvt_pk_bf16_f32 v134, v172, v173
	v_cvt_pk_bf16_f32 v135, v138, v139
	v_cvt_pk_bf16_f32 v136, v176, v177
	v_cvt_pk_bf16_f32 v137, v174, v175
	v_cvt_pk_bf16_f32 v138, v180, v181
	v_cvt_pk_bf16_f32 v139, v178, v179
	global_store_dwordx4 v[170:171], v[132:135], off
	global_store_dwordx4 v[170:171], v[136:139], off offset:256
	s_nop 1
	v_mov_b32_e32 v132, v230
	v_mov_b32_e32 v133, v231
	v_mov_b32_e32 v134, v232
	v_mov_b32_e32 v135, v233
	v_add_u32_e32 v140, 0xb0, v168
	v_ashrrev_i32_e32 v141, 31, v140
	v_mov_b32_e32 v136, v133
	v_mov_b32_e32 v137, v134
	v_mov_b32_e32 v133, v135
	v_pk_add_f32 v[132:133], v[136:137], v[132:133]
	s_nop 0
	v_add_f32_e32 v131, v132, v133
	v_fmamk_f32 v131, v131, 0x3a800000, v184
	v_rsq_f32_e32 v131, v131
	v_lshlrev_b64 v[132:133], 10, v[142:143]
	v_lshl_add_u64 v[170:171], v[128:129], 0, v[132:133]
	v_lshl_add_u64 v[142:143], v[140:141], 4, s[48:49]
	v_mul_f32_e32 v132, v130, v131
	v_pk_mul_f32 v[134:135], v[38:39], v[132:133] op_sel_hi:[1,0]
	v_pk_mul_f32 v[136:137], v[36:37], v[132:133] op_sel_hi:[1,0]
	v_pk_mul_f32 v[138:139], v[30:31], v[132:133] op_sel_hi:[1,0]
	v_pk_mul_f32 v[172:173], v[28:29], v[132:133] op_sel_hi:[1,0]
	v_pk_mul_f32 v[174:175], v[18:19], v[132:133] op_sel_hi:[1,0]
	v_pk_mul_f32 v[176:177], v[16:17], v[132:133] op_sel_hi:[1,0]
	v_pk_mul_f32 v[178:179], v[10:11], v[132:133] op_sel_hi:[1,0]
	v_pk_mul_f32 v[180:181], v[8:9], v[132:133] op_sel_hi:[1,0]
	v_cvt_pk_bf16_f32 v132, v136, v137
	v_cvt_pk_bf16_f32 v133, v134, v135
	v_cvt_pk_bf16_f32 v134, v172, v173
	v_cvt_pk_bf16_f32 v135, v138, v139
	v_cvt_pk_bf16_f32 v136, v176, v177
	v_cvt_pk_bf16_f32 v137, v174, v175
	v_cvt_pk_bf16_f32 v138, v180, v181
	v_cvt_pk_bf16_f32 v139, v178, v179
	global_store_dwordx4 v[170:171], v[132:135], off
	global_store_dwordx4 v[170:171], v[136:139], off offset:256
	s_nop 1
	v_mov_b32_e32 v132, v234
	v_mov_b32_e32 v133, v235
	v_mov_b32_e32 v134, v236
	v_mov_b32_e32 v135, v237
	v_mov_b32_e32 v136, v133
	v_mov_b32_e32 v137, v134
	v_mov_b32_e32 v133, v135
	v_pk_add_f32 v[132:133], v[136:137], v[132:133]
	s_nop 0
	v_add_f32_e32 v131, v132, v133
	v_fmamk_f32 v131, v131, 0x3a800000, v184
	v_rsq_f32_e32 v131, v131
	v_lshlrev_b64 v[132:133], 10, v[140:141]
	v_lshl_add_u64 v[136:137], v[128:129], 0, v[132:133]
	v_mul_f32_e32 v128, v130, v131
	v_pk_mul_f32 v[130:131], v[22:23], v[128:129] op_sel_hi:[1,0]
	v_pk_mul_f32 v[132:133], v[20:21], v[128:129] op_sel_hi:[1,0]
	v_pk_mul_f32 v[134:135], v[14:15], v[128:129] op_sel_hi:[1,0]
	v_pk_mul_f32 v[138:139], v[12:13], v[128:129] op_sel_hi:[1,0]
	v_pk_mul_f32 v[140:141], v[6:7], v[128:129] op_sel_hi:[1,0]
	v_pk_mul_f32 v[142:143], v[4:5], v[128:129] op_sel_hi:[1,0]
	v_pk_mul_f32 v[170:171], v[2:3], v[128:129] op_sel_hi:[1,0]
	v_pk_mul_f32 v[172:173], v[0:1], v[128:129] op_sel_hi:[1,0]
	v_cvt_pk_bf16_f32 v128, v132, v133
	v_cvt_pk_bf16_f32 v129, v130, v131
	v_cvt_pk_bf16_f32 v130, v138, v139
	v_cvt_pk_bf16_f32 v131, v134, v135
	v_cvt_pk_bf16_f32 v132, v142, v143
	v_cvt_pk_bf16_f32 v133, v140, v141
	v_cvt_pk_bf16_f32 v134, v172, v173
	v_cvt_pk_bf16_f32 v135, v170, v171
	global_store_dwordx4 v[136:137], v[128:131], off
	global_store_dwordx4 v[136:137], v[132:135], off offset:256

.LBB0_1096:
	v_lshl_add_u32 v140, s2, 8, v142
	v_lshl_or_b32 v138, s3, 8, v154
	v_ashrrev_i32_e32 v141, 31, v140
	v_lshlrev_b64 v[156:157], 12, v[140:141]
	v_ashrrev_i32_e32 v139, 31, v138
	v_lshl_add_u64 v[156:157], s[42:43], 0, v[156:157]
	v_lshlrev_b64 v[138:139], 1, v[138:139]
	v_lshl_add_u64 v[162:163], v[156:157], 0, v[138:139]
	v_mov_b32_e32 v204, 0x8000
	v_mov_b32_e32 v205, 0
	v_mov_b32_e32 v206, 0x28000
	v_mov_b32_e32 v207, 0
	v_mov_b32_e32 v166, v162
	v_mov_b32_e32 v167, v163
	global_load_dwordx4 v[208:211], v[166:167], off
	global_load_dwordx4 v[212:215], v[166:167], off offset:256
	v_lshl_add_u64 v[166:167], v[204:205], 1, v[166:167]
	global_load_dwordx4 v[216:219], v[166:167], off
	global_load_dwordx4 v[220:223], v[166:167], off offset:256
	v_lshl_add_u64 v[166:167], v[204:205], 1, v[166:167]
	global_load_dwordx4 v[224:227], v[166:167], off
	global_load_dwordx4 v[228:231], v[166:167], off offset:256
	v_lshl_add_u64 v[166:167], v[204:205], 1, v[166:167]
	global_load_dwordx4 v[232:235], v[166:167], off
	global_load_dwordx4 v[236:239], v[166:167], off offset:256
	v_lshlrev_b64 v[160:161], 11, v[140:141]
	s_mov_b64 s[2:3], -1
	s_andn2_b64 vcc, exec, s[38:39]
	s_waitcnt vmcnt(7)
	s_nop 1
	v_mov_b32_e32 v156, v208
	v_mov_b32_e32 v157, v209
	v_mov_b32_e32 v158, v210
	v_mov_b32_e32 v159, v211
	v_lshl_add_u64 v[166:167], v[206:207], 1, v[166:167]
	global_load_dwordx4 v[208:211], v[166:167], off
	v_lshlrev_b32_e32 v164, 16, v156
	v_and_b32_e32 v165, 0xffff0000, v156
	v_lshlrev_b32_e32 v156, 16, v157
	v_and_b32_e32 v157, 0xffff0000, v157
	v_pk_mul_f32 v[126:127], v[126:127], v[156:157]
	v_lshlrev_b32_e32 v156, 16, v158
	v_and_b32_e32 v157, 0xffff0000, v158
	v_pk_mul_f32 v[124:125], v[124:125], v[164:165]
	v_pk_mul_f32 v[156:157], v[120:121], v[156:157]
	v_lshlrev_b32_e32 v120, 16, v159
	v_and_b32_e32 v121, 0xffff0000, v159
	v_pk_mul_f32 v[158:159], v[122:123], v[120:121]
	v_cvt_pk_bf16_f32 v120, v124, v125
	v_lshl_add_u64 v[124:125], s[40:41], 0, v[160:161]
	v_cvt_pk_bf16_f32 v121, v126, v127
	v_cvt_pk_bf16_f32 v122, v156, v157
	v_cvt_pk_bf16_f32 v123, v158, v159
	v_lshl_add_u64 v[124:125], v[124:125], 0, v[138:139]
	global_store_dwordx4 v[124:125], v[120:123], off
	s_waitcnt vmcnt(8)
	s_nop 1
	v_mov_b32_e32 v120, v212
	v_mov_b32_e32 v121, v213
	v_mov_b32_e32 v122, v214
	v_mov_b32_e32 v123, v215
	global_load_dwordx4 v[212:215], v[166:167], off offset:256
	v_lshlrev_b32_e32 v126, 16, v120
	v_and_b32_e32 v127, 0xffff0000, v120
	v_lshlrev_b32_e32 v120, 16, v121
	v_and_b32_e32 v121, 0xffff0000, v121
	v_pk_mul_f32 v[118:119], v[118:119], v[120:121]
	v_lshlrev_b32_e32 v120, 16, v122
	v_and_b32_e32 v121, 0xffff0000, v122
	v_pk_mul_f32 v[120:121], v[112:113], v[120:121]
	v_lshlrev_b32_e32 v112, 16, v123
	v_and_b32_e32 v113, 0xffff0000, v123
	v_pk_mul_f32 v[116:117], v[116:117], v[126:127]
	v_pk_mul_f32 v[122:123], v[114:115], v[112:113]
	v_cvt_pk_bf16_f32 v112, v116, v117
	v_cvt_pk_bf16_f32 v113, v118, v119
	v_cvt_pk_bf16_f32 v114, v120, v121
	v_cvt_pk_bf16_f32 v115, v122, v123
	global_store_dwordx4 v[124:125], v[112:115], off offset:256
	s_nop 1
	v_or_b32_e32 v112, 16, v140
	v_ashrrev_i32_e32 v113, 31, v112
	v_lshlrev_b64 v[114:115], 12, v[112:113]
	v_lshlrev_b64 v[116:117], 11, v[112:113]
	v_lshl_add_u64 v[112:113], s[42:43], 0, v[114:115]
	v_lshl_add_u64 v[118:119], v[112:113], 0, v[138:139]
	s_waitcnt vmcnt(9)
	s_nop 1
	v_mov_b32_e32 v112, v216
	v_mov_b32_e32 v113, v217
	v_mov_b32_e32 v114, v218
	v_mov_b32_e32 v115, v219
	v_lshl_add_u64 v[166:167], v[204:205], 1, v[166:167]
	global_load_dwordx4 v[216:219], v[166:167], off
	v_lshlrev_b32_e32 v120, 16, v112
	v_and_b32_e32 v121, 0xffff0000, v112
	v_lshlrev_b32_e32 v112, 16, v113
	v_and_b32_e32 v113, 0xffff0000, v113
	v_pk_mul_f32 v[110:111], v[110:111], v[112:113]
	v_lshlrev_b32_e32 v112, 16, v114
	v_and_b32_e32 v113, 0xffff0000, v114
	v_pk_mul_f32 v[108:109], v[108:109], v[120:121]
	v_pk_mul_f32 v[112:113], v[104:105], v[112:113]
	v_lshlrev_b32_e32 v104, 16, v115
	v_and_b32_e32 v105, 0xffff0000, v115
	v_pk_mul_f32 v[114:115], v[106:107], v[104:105]
	v_cvt_pk_bf16_f32 v104, v108, v109
	v_lshl_add_u64 v[108:109], s[40:41], 0, v[116:117]
	v_cvt_pk_bf16_f32 v105, v110, v111
	v_cvt_pk_bf16_f32 v106, v112, v113
	v_cvt_pk_bf16_f32 v107, v114, v115
	v_lshl_add_u64 v[108:109], v[108:109], 0, v[138:139]
	global_store_dwordx4 v[108:109], v[104:107], off
	s_waitcnt vmcnt(10)
	s_nop 1
	v_mov_b32_e32 v104, v220
	v_mov_b32_e32 v105, v221
	v_mov_b32_e32 v106, v222
	v_mov_b32_e32 v107, v223
	global_load_dwordx4 v[220:223], v[166:167], off offset:256
	v_lshlrev_b32_e32 v110, 16, v104
	v_and_b32_e32 v111, 0xffff0000, v104
	v_lshlrev_b32_e32 v104, 16, v105
	v_and_b32_e32 v105, 0xffff0000, v105
	v_pk_mul_f32 v[102:103], v[102:103], v[104:105]
	v_lshlrev_b32_e32 v104, 16, v106
	v_and_b32_e32 v105, 0xffff0000, v106
	v_pk_mul_f32 v[104:105], v[96:97], v[104:105]
	v_lshlrev_b32_e32 v96, 16, v107
	v_and_b32_e32 v97, 0xffff0000, v107
	v_pk_mul_f32 v[100:101], v[100:101], v[110:111]
	v_pk_mul_f32 v[106:107], v[98:99], v[96:97]
	v_cvt_pk_bf16_f32 v96, v100, v101
	v_cvt_pk_bf16_f32 v97, v102, v103
	v_cvt_pk_bf16_f32 v98, v104, v105
	v_cvt_pk_bf16_f32 v99, v106, v107
	global_store_dwordx4 v[108:109], v[96:99], off offset:256
	s_nop 1
	v_or_b32_e32 v96, 32, v140
	v_ashrrev_i32_e32 v97, 31, v96
	v_lshlrev_b64 v[98:99], 12, v[96:97]
	v_lshlrev_b64 v[100:101], 11, v[96:97]
	v_lshl_add_u64 v[96:97], s[42:43], 0, v[98:99]
	v_lshl_add_u64 v[102:103], v[96:97], 0, v[138:139]
	s_waitcnt vmcnt(11)
	s_nop 1
	v_mov_b32_e32 v96, v224
	v_mov_b32_e32 v97, v225
	v_mov_b32_e32 v98, v226
	v_mov_b32_e32 v99, v227
	v_lshl_add_u64 v[166:167], v[204:205], 1, v[166:167]
	global_load_dwordx4 v[224:227], v[166:167], off
	v_lshlrev_b32_e32 v104, 16, v96
	v_and_b32_e32 v105, 0xffff0000, v96
	v_lshlrev_b32_e32 v96, 16, v97
	v_and_b32_e32 v97, 0xffff0000, v97
	v_pk_mul_f32 v[94:95], v[94:95], v[96:97]
	v_lshlrev_b32_e32 v96, 16, v98
	v_and_b32_e32 v97, 0xffff0000, v98
	v_pk_mul_f32 v[92:93], v[92:93], v[104:105]
	v_pk_mul_f32 v[96:97], v[88:89], v[96:97]
	v_lshlrev_b32_e32 v88, 16, v99
	v_and_b32_e32 v89, 0xffff0000, v99
	v_pk_mul_f32 v[98:99], v[90:91], v[88:89]
	v_cvt_pk_bf16_f32 v88, v92, v93
	v_lshl_add_u64 v[92:93], s[40:41], 0, v[100:101]
	v_cvt_pk_bf16_f32 v89, v94, v95
	v_cvt_pk_bf16_f32 v90, v96, v97
	v_cvt_pk_bf16_f32 v91, v98, v99
	v_lshl_add_u64 v[92:93], v[92:93], 0, v[138:139]
	global_store_dwordx4 v[92:93], v[88:91], off
	s_waitcnt vmcnt(12)
	s_nop 1
	v_mov_b32_e32 v88, v228
	v_mov_b32_e32 v89, v229
	v_mov_b32_e32 v90, v230
	v_mov_b32_e32 v91, v231
	global_load_dwordx4 v[228:231], v[166:167], off offset:256
	v_lshlrev_b32_e32 v94, 16, v88
	v_and_b32_e32 v95, 0xffff0000, v88
	v_lshlrev_b32_e32 v88, 16, v89
	v_and_b32_e32 v89, 0xffff0000, v89
	v_pk_mul_f32 v[86:87], v[86:87], v[88:89]
	v_lshlrev_b32_e32 v88, 16, v90
	v_and_b32_e32 v89, 0xffff0000, v90
	v_pk_mul_f32 v[88:89], v[80:81], v[88:89]
	v_lshlrev_b32_e32 v80, 16, v91
	v_and_b32_e32 v81, 0xffff0000, v91
	v_pk_mul_f32 v[84:85], v[84:85], v[94:95]
	v_pk_mul_f32 v[90:91], v[82:83], v[80:81]
	v_cvt_pk_bf16_f32 v80, v84, v85
	v_cvt_pk_bf16_f32 v81, v86, v87
	v_cvt_pk_bf16_f32 v82, v88, v89
	v_cvt_pk_bf16_f32 v83, v90, v91
	global_store_dwordx4 v[92:93], v[80:83], off offset:256
	s_nop 1
	v_or_b32_e32 v80, 48, v140
	v_ashrrev_i32_e32 v81, 31, v80
	v_lshlrev_b64 v[82:83], 12, v[80:81]
	v_lshlrev_b64 v[84:85], 11, v[80:81]
	v_lshl_add_u64 v[80:81], s[42:43], 0, v[82:83]
	v_lshl_add_u64 v[86:87], v[80:81], 0, v[138:139]
	s_waitcnt vmcnt(13)
	s_nop 1
	v_mov_b32_e32 v80, v232
	v_mov_b32_e32 v81, v233
	v_mov_b32_e32 v82, v234
	v_mov_b32_e32 v83, v235
	v_lshl_add_u64 v[166:167], v[204:205], 1, v[166:167]
	global_load_dwordx4 v[232:235], v[166:167], off
	v_lshlrev_b32_e32 v88, 16, v80
	v_and_b32_e32 v89, 0xffff0000, v80
	v_lshlrev_b32_e32 v80, 16, v81
	v_and_b32_e32 v81, 0xffff0000, v81
	v_pk_mul_f32 v[78:79], v[78:79], v[80:81]
	v_lshlrev_b32_e32 v80, 16, v82
	v_and_b32_e32 v81, 0xffff0000, v82
	v_pk_mul_f32 v[76:77], v[76:77], v[88:89]
	v_pk_mul_f32 v[80:81], v[72:73], v[80:81]
	v_lshlrev_b32_e32 v72, 16, v83
	v_and_b32_e32 v73, 0xffff0000, v83
	v_pk_mul_f32 v[82:83], v[74:75], v[72:73]
	v_cvt_pk_bf16_f32 v72, v76, v77
	v_lshl_add_u64 v[76:77], s[40:41], 0, v[84:85]
	v_cvt_pk_bf16_f32 v73, v78, v79
	v_cvt_pk_bf16_f32 v74, v80, v81
	v_cvt_pk_bf16_f32 v75, v82, v83
	v_lshl_add_u64 v[76:77], v[76:77], 0, v[138:139]
	global_store_dwordx4 v[76:77], v[72:75], off
	s_waitcnt vmcnt(14)
	s_nop 1
	v_mov_b32_e32 v72, v236
	v_mov_b32_e32 v73, v237
	v_mov_b32_e32 v74, v238
	v_mov_b32_e32 v75, v239
	global_load_dwordx4 v[236:239], v[166:167], off offset:256
	v_lshlrev_b32_e32 v78, 16, v72
	v_and_b32_e32 v79, 0xffff0000, v72
	v_lshlrev_b32_e32 v72, 16, v73
	v_and_b32_e32 v73, 0xffff0000, v73
	v_pk_mul_f32 v[70:71], v[70:71], v[72:73]
	v_lshlrev_b32_e32 v72, 16, v74
	v_and_b32_e32 v73, 0xffff0000, v74
	v_pk_mul_f32 v[72:73], v[64:65], v[72:73]
	v_lshlrev_b32_e32 v64, 16, v75
	v_and_b32_e32 v65, 0xffff0000, v75
	v_pk_mul_f32 v[68:69], v[68:69], v[78:79]
	v_pk_mul_f32 v[74:75], v[66:67], v[64:65]
	v_cvt_pk_bf16_f32 v64, v68, v69
	v_cvt_pk_bf16_f32 v65, v70, v71
	v_cvt_pk_bf16_f32 v66, v72, v73
	v_cvt_pk_bf16_f32 v67, v74, v75
	global_store_dwordx4 v[76:77], v[64:67], off offset:256
	s_nop 1
	v_add_u32_e32 v64, 0x80, v140
	v_ashrrev_i32_e32 v65, 31, v64
	v_lshlrev_b64 v[66:67], 12, v[64:65]
	v_lshlrev_b64 v[68:69], 11, v[64:65]
	v_lshl_add_u64 v[64:65], s[42:43], 0, v[66:67]
	v_lshl_add_u64 v[70:71], v[64:65], 0, v[138:139]
	s_waitcnt vmcnt(15)
	s_nop 1
	v_mov_b32_e32 v64, v208
	v_mov_b32_e32 v65, v209
	v_mov_b32_e32 v66, v210
	v_mov_b32_e32 v67, v211
	v_lshlrev_b32_e32 v72, 16, v64
	v_and_b32_e32 v73, 0xffff0000, v64
	v_lshlrev_b32_e32 v64, 16, v65
	v_and_b32_e32 v65, 0xffff0000, v65
	v_pk_mul_f32 v[62:63], v[62:63], v[64:65]
	v_lshlrev_b32_e32 v64, 16, v66
	v_and_b32_e32 v65, 0xffff0000, v66
	v_pk_mul_f32 v[60:61], v[60:61], v[72:73]
	v_pk_mul_f32 v[64:65], v[56:57], v[64:65]
	v_lshlrev_b32_e32 v56, 16, v67
	v_and_b32_e32 v57, 0xffff0000, v67
	v_pk_mul_f32 v[66:67], v[58:59], v[56:57]
	v_cvt_pk_bf16_f32 v56, v60, v61
	v_lshl_add_u64 v[60:61], s[40:41], 0, v[68:69]
	v_cvt_pk_bf16_f32 v57, v62, v63
	v_cvt_pk_bf16_f32 v58, v64, v65
	v_cvt_pk_bf16_f32 v59, v66, v67
	v_lshl_add_u64 v[60:61], v[60:61], 0, v[138:139]
	global_store_dwordx4 v[60:61], v[56:59], off
	s_waitcnt vmcnt(14)
	s_nop 1
	v_mov_b32_e32 v56, v212
	v_mov_b32_e32 v57, v213
	v_mov_b32_e32 v58, v214
	v_mov_b32_e32 v59, v215
	v_lshlrev_b32_e32 v62, 16, v56
	v_and_b32_e32 v63, 0xffff0000, v56
	v_lshlrev_b32_e32 v56, 16, v57
	v_and_b32_e32 v57, 0xffff0000, v57
	v_pk_mul_f32 v[54:55], v[54:55], v[56:57]
	v_lshlrev_b32_e32 v56, 16, v58
	v_and_b32_e32 v57, 0xffff0000, v58
	v_pk_mul_f32 v[56:57], v[48:49], v[56:57]
	v_lshlrev_b32_e32 v48, 16, v59
	v_and_b32_e32 v49, 0xffff0000, v59
	v_pk_mul_f32 v[52:53], v[52:53], v[62:63]
	v_pk_mul_f32 v[58:59], v[50:51], v[48:49]
	v_cvt_pk_bf16_f32 v48, v52, v53
	v_cvt_pk_bf16_f32 v49, v54, v55
	v_cvt_pk_bf16_f32 v50, v56, v57
	v_cvt_pk_bf16_f32 v51, v58, v59
	global_store_dwordx4 v[60:61], v[48:51], off offset:256
	s_nop 1
	v_add_u32_e32 v48, 0x90, v140
	v_ashrrev_i32_e32 v49, 31, v48
	v_lshlrev_b64 v[50:51], 12, v[48:49]
	v_lshlrev_b64 v[52:53], 11, v[48:49]
	v_lshl_add_u64 v[48:49], s[42:43], 0, v[50:51]
	v_lshl_add_u64 v[54:55], v[48:49], 0, v[138:139]
	s_waitcnt vmcnt(13)
	s_nop 1
	v_mov_b32_e32 v48, v216
	v_mov_b32_e32 v49, v217
	v_mov_b32_e32 v50, v218
	v_mov_b32_e32 v51, v219
	v_lshlrev_b32_e32 v56, 16, v48
	v_and_b32_e32 v57, 0xffff0000, v48
	v_lshlrev_b32_e32 v48, 16, v49
	v_and_b32_e32 v49, 0xffff0000, v49
	v_pk_mul_f32 v[46:47], v[46:47], v[48:49]
	v_lshlrev_b32_e32 v48, 16, v50
	v_and_b32_e32 v49, 0xffff0000, v50
	v_pk_mul_f32 v[44:45], v[44:45], v[56:57]
	v_pk_mul_f32 v[48:49], v[40:41], v[48:49]
	v_lshlrev_b32_e32 v40, 16, v51
	v_and_b32_e32 v41, 0xffff0000, v51
	v_pk_mul_f32 v[50:51], v[42:43], v[40:41]
	v_cvt_pk_bf16_f32 v40, v44, v45
	v_lshl_add_u64 v[44:45], s[40:41], 0, v[52:53]
	v_cvt_pk_bf16_f32 v41, v46, v47
	v_cvt_pk_bf16_f32 v42, v48, v49
	v_cvt_pk_bf16_f32 v43, v50, v51
	v_lshl_add_u64 v[44:45], v[44:45], 0, v[138:139]
	global_store_dwordx4 v[44:45], v[40:43], off
	s_waitcnt vmcnt(12)
	s_nop 1
	v_mov_b32_e32 v40, v220
	v_mov_b32_e32 v41, v221
	v_mov_b32_e32 v42, v222
	v_mov_b32_e32 v43, v223
	v_lshlrev_b32_e32 v46, 16, v40
	v_and_b32_e32 v47, 0xffff0000, v40
	v_lshlrev_b32_e32 v40, 16, v41
	v_and_b32_e32 v41, 0xffff0000, v41
	v_pk_mul_f32 v[38:39], v[38:39], v[40:41]
	v_lshlrev_b32_e32 v40, 16, v42
	v_and_b32_e32 v41, 0xffff0000, v42
	v_pk_mul_f32 v[40:41], v[32:33], v[40:41]
	v_lshlrev_b32_e32 v32, 16, v43
	v_and_b32_e32 v33, 0xffff0000, v43
	v_pk_mul_f32 v[36:37], v[36:37], v[46:47]
	v_pk_mul_f32 v[42:43], v[34:35], v[32:33]
	v_cvt_pk_bf16_f32 v32, v36, v37
	v_cvt_pk_bf16_f32 v33, v38, v39
	v_cvt_pk_bf16_f32 v34, v40, v41
	v_cvt_pk_bf16_f32 v35, v42, v43
	global_store_dwordx4 v[44:45], v[32:35], off offset:256
	s_nop 1
	v_add_u32_e32 v32, 0xa0, v140
	v_ashrrev_i32_e32 v33, 31, v32
	v_lshlrev_b64 v[34:35], 12, v[32:33]
	v_lshlrev_b64 v[36:37], 11, v[32:33]
	v_lshl_add_u64 v[32:33], s[42:43], 0, v[34:35]
	v_lshl_add_u64 v[38:39], v[32:33], 0, v[138:139]
	s_waitcnt vmcnt(11)
	s_nop 1
	v_mov_b32_e32 v32, v224
	v_mov_b32_e32 v33, v225
	v_mov_b32_e32 v34, v226
	v_mov_b32_e32 v35, v227
	v_lshlrev_b32_e32 v40, 16, v32
	v_and_b32_e32 v41, 0xffff0000, v32
	v_lshlrev_b32_e32 v32, 16, v33
	v_and_b32_e32 v33, 0xffff0000, v33
	v_pk_mul_f32 v[30:31], v[30:31], v[32:33]
	v_lshlrev_b32_e32 v32, 16, v34
	v_and_b32_e32 v33, 0xffff0000, v34
	v_pk_mul_f32 v[28:29], v[28:29], v[40:41]
	v_pk_mul_f32 v[32:33], v[24:25], v[32:33]
	v_lshlrev_b32_e32 v24, 16, v35
	v_and_b32_e32 v25, 0xffff0000, v35
	v_pk_mul_f32 v[34:35], v[26:27], v[24:25]
	v_cvt_pk_bf16_f32 v24, v28, v29
	v_lshl_add_u64 v[28:29], s[40:41], 0, v[36:37]
	v_cvt_pk_bf16_f32 v25, v30, v31
	v_cvt_pk_bf16_f32 v26, v32, v33
	v_cvt_pk_bf16_f32 v27, v34, v35
	v_lshl_add_u64 v[28:29], v[28:29], 0, v[138:139]
	global_store_dwordx4 v[28:29], v[24:27], off
	s_waitcnt vmcnt(10)
	s_nop 1
	v_mov_b32_e32 v24, v228
	v_mov_b32_e32 v25, v229
	v_mov_b32_e32 v26, v230
	v_mov_b32_e32 v27, v231
	v_lshlrev_b32_e32 v30, 16, v24
	v_and_b32_e32 v31, 0xffff0000, v24
	v_lshlrev_b32_e32 v24, 16, v25
	v_and_b32_e32 v25, 0xffff0000, v25
	v_pk_mul_f32 v[22:23], v[22:23], v[24:25]
	v_lshlrev_b32_e32 v24, 16, v26
	v_and_b32_e32 v25, 0xffff0000, v26
	v_pk_mul_f32 v[24:25], v[16:17], v[24:25]
	v_lshlrev_b32_e32 v16, 16, v27
	v_and_b32_e32 v17, 0xffff0000, v27
	v_pk_mul_f32 v[20:21], v[20:21], v[30:31]
	v_pk_mul_f32 v[26:27], v[18:19], v[16:17]
	v_cvt_pk_bf16_f32 v16, v20, v21
	v_cvt_pk_bf16_f32 v17, v22, v23
	v_cvt_pk_bf16_f32 v18, v24, v25
	v_cvt_pk_bf16_f32 v19, v26, v27
	global_store_dwordx4 v[28:29], v[16:19], off offset:256
	s_nop 1
	v_add_u32_e32 v16, 0xb0, v140
	v_ashrrev_i32_e32 v17, 31, v16
	v_lshlrev_b64 v[18:19], 12, v[16:17]
	v_lshlrev_b64 v[20:21], 11, v[16:17]
	v_lshl_add_u64 v[16:17], s[42:43], 0, v[18:19]
	v_lshl_add_u64 v[22:23], v[16:17], 0, v[138:139]
	s_waitcnt vmcnt(9)
	s_nop 1
	v_mov_b32_e32 v16, v232
	v_mov_b32_e32 v17, v233
	v_mov_b32_e32 v18, v234
	v_mov_b32_e32 v19, v235
	v_lshlrev_b32_e32 v24, 16, v16
	v_and_b32_e32 v25, 0xffff0000, v16
	v_lshlrev_b32_e32 v16, 16, v17
	v_and_b32_e32 v17, 0xffff0000, v17
	v_pk_mul_f32 v[14:15], v[14:15], v[16:17]
	v_lshlrev_b32_e32 v16, 16, v18
	v_and_b32_e32 v17, 0xffff0000, v18
	v_pk_mul_f32 v[12:13], v[12:13], v[24:25]
	v_pk_mul_f32 v[16:17], v[8:9], v[16:17]
	v_lshlrev_b32_e32 v8, 16, v19
	v_and_b32_e32 v9, 0xffff0000, v19
	v_pk_mul_f32 v[18:19], v[10:11], v[8:9]
	v_cvt_pk_bf16_f32 v8, v12, v13
	v_lshl_add_u64 v[12:13], s[40:41], 0, v[20:21]
	v_cvt_pk_bf16_f32 v9, v14, v15
	v_cvt_pk_bf16_f32 v10, v16, v17
	v_cvt_pk_bf16_f32 v11, v18, v19
	v_lshl_add_u64 v[12:13], v[12:13], 0, v[138:139]
	global_store_dwordx4 v[12:13], v[8:11], off
	s_waitcnt vmcnt(8)
	s_nop 1
	v_mov_b32_e32 v8, v236
	v_mov_b32_e32 v9, v237
	v_mov_b32_e32 v10, v238
	v_mov_b32_e32 v11, v239
	v_lshlrev_b32_e32 v14, 16, v8
	v_and_b32_e32 v15, 0xffff0000, v8
	v_lshlrev_b32_e32 v8, 16, v9
	v_and_b32_e32 v9, 0xffff0000, v9
	v_pk_mul_f32 v[6:7], v[6:7], v[8:9]
	v_lshlrev_b32_e32 v8, 16, v10
	v_and_b32_e32 v9, 0xffff0000, v10
	v_pk_mul_f32 v[8:9], v[0:1], v[8:9]
	v_lshlrev_b32_e32 v0, 16, v11
	v_and_b32_e32 v1, 0xffff0000, v11
	v_pk_mul_f32 v[4:5], v[4:5], v[14:15]
	v_pk_mul_f32 v[10:11], v[2:3], v[0:1]
	v_cvt_pk_bf16_f32 v0, v4, v5
	v_cvt_pk_bf16_f32 v1, v6, v7
	v_cvt_pk_bf16_f32 v2, v8, v9
	v_cvt_pk_bf16_f32 v3, v10, v11
	global_store_dwordx4 v[12:13], v[0:3], off offset:256
	s_cbranch_vccnz .LBB0_1085
	s_andn2_b64 vcc, exec, s[44:45]
	s_cbranch_vccnz .LBB0_1084
	s_barrier
	s_branch .LBB0_1084

.LBB0_1120:
	v_lshl_add_u32 v140, s2, 8, v142
	v_lshl_or_b32 v138, s3, 8, v154
	v_ashrrev_i32_e32 v141, 31, v140
	v_lshlrev_b64 v[156:157], 12, v[140:141]
	v_lshlrev_b64 v[160:161], 11, v[140:141]
	v_ashrrev_i32_e32 v139, 31, v138
	v_lshl_add_u64 v[156:157], s[42:43], 0, v[156:157]
	v_lshlrev_b64 v[138:139], 1, v[138:139]
	v_lshl_add_u64 v[160:161], s[40:41], 0, v[160:161]
	v_lshl_add_u64 v[164:165], v[156:157], 0, v[138:139]
	v_lshl_add_u64 v[166:167], v[160:161], 0, v[138:139]
	v_mov_b32_e32 v204, 0x8000
	v_mov_b32_e32 v205, 0
	v_mov_b32_e32 v206, 0x28000
	v_mov_b32_e32 v207, 0
	v_mov_b32_e32 v172, v164
	v_mov_b32_e32 v173, v165
	v_mov_b32_e32 v174, v166
	v_mov_b32_e32 v175, v167
	global_load_dwordx4 v[208:211], v[172:173], off offset:2048
	global_load_dwordx4 v[212:215], v[174:175], off
	global_load_dwordx4 v[216:219], v[172:173], off offset:2304
	global_load_dwordx4 v[220:223], v[174:175], off offset:256
	v_lshl_add_u64 v[172:173], v[204:205], 1, v[172:173]
	v_lshl_add_u64 v[174:175], v[204:205], 0, v[174:175]
	global_load_dwordx4 v[224:227], v[172:173], off offset:2048
	global_load_dwordx4 v[228:231], v[174:175], off
	global_load_dwordx4 v[232:235], v[172:173], off offset:2304
	global_load_dwordx4 v[236:239], v[174:175], off offset:256
	s_mov_b64 s[2:3], -1
	s_andn2_b64 vcc, exec, s[38:39]
	s_waitcnt vmcnt(6)
	s_nop 1
	v_mov_b32_e32 v156, v208
	v_mov_b32_e32 v157, v209
	v_mov_b32_e32 v158, v210
	v_mov_b32_e32 v159, v211
	v_mov_b32_e32 v160, v212
	v_mov_b32_e32 v161, v213
	v_mov_b32_e32 v162, v214
	v_mov_b32_e32 v163, v215
	v_lshl_add_u64 v[172:173], v[204:205], 1, v[172:173]
	v_lshl_add_u64 v[174:175], v[204:205], 0, v[174:175]
	global_load_dwordx4 v[208:211], v[172:173], off offset:2048
	global_load_dwordx4 v[212:215], v[174:175], off
	v_lshlrev_b32_e32 v168, 16, v156
	v_and_b32_e32 v169, 0xffff0000, v156
	v_lshlrev_b32_e32 v170, 16, v160
	v_and_b32_e32 v171, 0xffff0000, v160
	v_lshlrev_b32_e32 v156, 16, v157
	v_and_b32_e32 v157, 0xffff0000, v157
	v_lshlrev_b32_e32 v160, 16, v161
	v_and_b32_e32 v161, 0xffff0000, v161
	v_pk_fma_f32 v[126:127], v[126:127], v[156:157], v[160:161]
	v_lshlrev_b32_e32 v156, 16, v158
	v_and_b32_e32 v157, 0xffff0000, v158
	v_lshlrev_b32_e32 v160, 16, v162
	v_and_b32_e32 v161, 0xffff0000, v162
	v_pk_fma_f32 v[156:157], v[120:121], v[156:157], v[160:161]
	v_lshlrev_b32_e32 v120, 16, v159
	v_and_b32_e32 v121, 0xffff0000, v159
	v_lshlrev_b32_e32 v158, 16, v163
	v_and_b32_e32 v159, 0xffff0000, v163
	v_pk_fma_f32 v[124:125], v[124:125], v[168:169], v[170:171]
	v_pk_fma_f32 v[158:159], v[122:123], v[120:121], v[158:159]
	v_cvt_pk_bf16_f32 v120, v124, v125
	v_cvt_pk_bf16_f32 v121, v126, v127
	v_cvt_pk_bf16_f32 v122, v156, v157
	v_cvt_pk_bf16_f32 v123, v158, v159
	global_store_dwordx4 v[166:167], v[120:123], off
	s_nop 0
	s_waitcnt vmcnt(7)
	s_nop 1
	v_mov_b32_e32 v120, v216
	v_mov_b32_e32 v121, v217
	v_mov_b32_e32 v122, v218
	v_mov_b32_e32 v123, v219
	v_mov_b32_e32 v124, v220
	v_mov_b32_e32 v125, v221
	v_mov_b32_e32 v126, v222
	v_mov_b32_e32 v127, v223
	global_load_dwordx4 v[216:219], v[172:173], off offset:2304
	global_load_dwordx4 v[220:223], v[174:175], off offset:256
	v_lshlrev_b32_e32 v156, 16, v120
	v_and_b32_e32 v157, 0xffff0000, v120
	v_lshlrev_b32_e32 v158, 16, v124
	v_and_b32_e32 v159, 0xffff0000, v124
	v_lshlrev_b32_e32 v120, 16, v121
	v_and_b32_e32 v121, 0xffff0000, v121
	v_lshlrev_b32_e32 v124, 16, v125
	v_and_b32_e32 v125, 0xffff0000, v125
	v_pk_fma_f32 v[118:119], v[118:119], v[120:121], v[124:125]
	v_lshlrev_b32_e32 v120, 16, v122
	v_and_b32_e32 v121, 0xffff0000, v122
	v_lshlrev_b32_e32 v124, 16, v126
	v_and_b32_e32 v125, 0xffff0000, v126
	v_pk_fma_f32 v[120:121], v[112:113], v[120:121], v[124:125]
	v_lshlrev_b32_e32 v112, 16, v123
	v_and_b32_e32 v113, 0xffff0000, v123
	v_lshlrev_b32_e32 v122, 16, v127
	v_and_b32_e32 v123, 0xffff0000, v127
	v_pk_fma_f32 v[116:117], v[116:117], v[156:157], v[158:159]
	v_pk_fma_f32 v[122:123], v[114:115], v[112:113], v[122:123]
	v_cvt_pk_bf16_f32 v112, v116, v117
	v_cvt_pk_bf16_f32 v113, v118, v119
	v_cvt_pk_bf16_f32 v114, v120, v121
	v_cvt_pk_bf16_f32 v115, v122, v123
	global_store_dwordx4 v[166:167], v[112:115], off offset:256
	s_nop 1
	v_or_b32_e32 v112, 16, v140
	v_ashrrev_i32_e32 v113, 31, v112
	v_lshlrev_b64 v[114:115], 12, v[112:113]
	v_lshlrev_b64 v[116:117], 11, v[112:113]
	v_lshl_add_u64 v[112:113], s[42:43], 0, v[114:115]
	v_lshl_add_u64 v[116:117], s[40:41], 0, v[116:117]
	v_lshl_add_u64 v[120:121], v[112:113], 0, v[138:139]
	v_lshl_add_u64 v[122:123], v[116:117], 0, v[138:139]
	s_waitcnt vmcnt(8)
	s_nop 1
	v_mov_b32_e32 v112, v224
	v_mov_b32_e32 v113, v225
	v_mov_b32_e32 v114, v226
	v_mov_b32_e32 v115, v227
	v_mov_b32_e32 v116, v228
	v_mov_b32_e32 v117, v229
	v_mov_b32_e32 v118, v230
	v_mov_b32_e32 v119, v231
	v_lshl_add_u64 v[172:173], v[204:205], 1, v[172:173]
	v_lshl_add_u64 v[174:175], v[204:205], 0, v[174:175]
	global_load_dwordx4 v[224:227], v[172:173], off offset:2048
	global_load_dwordx4 v[228:231], v[174:175], off
	v_lshlrev_b32_e32 v124, 16, v112
	v_and_b32_e32 v125, 0xffff0000, v112
	v_lshlrev_b32_e32 v126, 16, v116
	v_and_b32_e32 v127, 0xffff0000, v116
	v_lshlrev_b32_e32 v112, 16, v113
	v_and_b32_e32 v113, 0xffff0000, v113
	v_lshlrev_b32_e32 v116, 16, v117
	v_and_b32_e32 v117, 0xffff0000, v117
	v_pk_fma_f32 v[110:111], v[110:111], v[112:113], v[116:117]
	v_lshlrev_b32_e32 v112, 16, v114
	v_and_b32_e32 v113, 0xffff0000, v114
	v_lshlrev_b32_e32 v116, 16, v118
	v_and_b32_e32 v117, 0xffff0000, v118
	v_pk_fma_f32 v[112:113], v[104:105], v[112:113], v[116:117]
	v_lshlrev_b32_e32 v104, 16, v115
	v_and_b32_e32 v105, 0xffff0000, v115
	v_lshlrev_b32_e32 v114, 16, v119
	v_and_b32_e32 v115, 0xffff0000, v119
	v_pk_fma_f32 v[108:109], v[108:109], v[124:125], v[126:127]
	v_pk_fma_f32 v[114:115], v[106:107], v[104:105], v[114:115]
	v_cvt_pk_bf16_f32 v104, v108, v109
	v_cvt_pk_bf16_f32 v105, v110, v111
	v_cvt_pk_bf16_f32 v106, v112, v113
	v_cvt_pk_bf16_f32 v107, v114, v115
	global_store_dwordx4 v[122:123], v[104:107], off
	s_nop 0
	s_waitcnt vmcnt(9)
	s_nop 1
	v_mov_b32_e32 v104, v232
	v_mov_b32_e32 v105, v233
	v_mov_b32_e32 v106, v234
	v_mov_b32_e32 v107, v235
	v_mov_b32_e32 v108, v236
	v_mov_b32_e32 v109, v237
	v_mov_b32_e32 v110, v238
	v_mov_b32_e32 v111, v239
	global_load_dwordx4 v[232:235], v[172:173], off offset:2304
	global_load_dwordx4 v[236:239], v[174:175], off offset:256
	v_lshlrev_b32_e32 v112, 16, v104
	v_and_b32_e32 v113, 0xffff0000, v104
	v_lshlrev_b32_e32 v114, 16, v108
	v_and_b32_e32 v115, 0xffff0000, v108
	v_lshlrev_b32_e32 v104, 16, v105
	v_and_b32_e32 v105, 0xffff0000, v105
	v_lshlrev_b32_e32 v108, 16, v109
	v_and_b32_e32 v109, 0xffff0000, v109
	v_pk_fma_f32 v[102:103], v[102:103], v[104:105], v[108:109]
	v_lshlrev_b32_e32 v104, 16, v106
	v_and_b32_e32 v105, 0xffff0000, v106
	v_lshlrev_b32_e32 v108, 16, v110
	v_and_b32_e32 v109, 0xffff0000, v110
	v_pk_fma_f32 v[104:105], v[96:97], v[104:105], v[108:109]
	v_lshlrev_b32_e32 v96, 16, v107
	v_and_b32_e32 v97, 0xffff0000, v107
	v_lshlrev_b32_e32 v106, 16, v111
	v_and_b32_e32 v107, 0xffff0000, v111
	v_pk_fma_f32 v[100:101], v[100:101], v[112:113], v[114:115]
	v_pk_fma_f32 v[106:107], v[98:99], v[96:97], v[106:107]
	v_cvt_pk_bf16_f32 v96, v100, v101
	v_cvt_pk_bf16_f32 v97, v102, v103
	v_cvt_pk_bf16_f32 v98, v104, v105
	v_cvt_pk_bf16_f32 v99, v106, v107
	global_store_dwordx4 v[122:123], v[96:99], off offset:256
	s_nop 1
	v_or_b32_e32 v96, 32, v140
	v_ashrrev_i32_e32 v97, 31, v96
	v_lshlrev_b64 v[98:99], 12, v[96:97]
	v_lshlrev_b64 v[100:101], 11, v[96:97]
	v_lshl_add_u64 v[96:97], s[42:43], 0, v[98:99]
	v_lshl_add_u64 v[100:101], s[40:41], 0, v[100:101]
	v_lshl_add_u64 v[104:105], v[96:97], 0, v[138:139]
	v_lshl_add_u64 v[106:107], v[100:101], 0, v[138:139]
	s_waitcnt vmcnt(10)
	s_nop 1
	v_mov_b32_e32 v96, v208
	v_mov_b32_e32 v97, v209
	v_mov_b32_e32 v98, v210
	v_mov_b32_e32 v99, v211
	v_mov_b32_e32 v100, v212
	v_mov_b32_e32 v101, v213
	v_mov_b32_e32 v102, v214
	v_mov_b32_e32 v103, v215
	v_lshl_add_u64 v[172:173], v[206:207], 1, v[172:173]
	v_lshl_add_u64 v[174:175], v[206:207], 0, v[174:175]
	global_load_dwordx4 v[208:211], v[172:173], off offset:2048
	global_load_dwordx4 v[212:215], v[174:175], off
	v_lshlrev_b32_e32 v108, 16, v96
	v_and_b32_e32 v109, 0xffff0000, v96
	v_lshlrev_b32_e32 v110, 16, v100
	v_and_b32_e32 v111, 0xffff0000, v100
	v_lshlrev_b32_e32 v96, 16, v97
	v_and_b32_e32 v97, 0xffff0000, v97
	v_lshlrev_b32_e32 v100, 16, v101
	v_and_b32_e32 v101, 0xffff0000, v101
	v_pk_fma_f32 v[94:95], v[94:95], v[96:97], v[100:101]
	v_lshlrev_b32_e32 v96, 16, v98
	v_and_b32_e32 v97, 0xffff0000, v98
	v_lshlrev_b32_e32 v100, 16, v102
	v_and_b32_e32 v101, 0xffff0000, v102
	v_pk_fma_f32 v[96:97], v[88:89], v[96:97], v[100:101]
	v_lshlrev_b32_e32 v88, 16, v99
	v_and_b32_e32 v89, 0xffff0000, v99
	v_lshlrev_b32_e32 v98, 16, v103
	v_and_b32_e32 v99, 0xffff0000, v103
	v_pk_fma_f32 v[92:93], v[92:93], v[108:109], v[110:111]
	v_pk_fma_f32 v[98:99], v[90:91], v[88:89], v[98:99]
	v_cvt_pk_bf16_f32 v88, v92, v93
	v_cvt_pk_bf16_f32 v89, v94, v95
	v_cvt_pk_bf16_f32 v90, v96, v97
	v_cvt_pk_bf16_f32 v91, v98, v99
	global_store_dwordx4 v[106:107], v[88:91], off
	s_nop 0
	s_waitcnt vmcnt(10)
	s_nop 1
	v_mov_b32_e32 v88, v216
	v_mov_b32_e32 v89, v217
	v_mov_b32_e32 v90, v218
	v_mov_b32_e32 v91, v219
	v_mov_b32_e32 v92, v220
	v_mov_b32_e32 v93, v221
	v_mov_b32_e32 v94, v222
	v_mov_b32_e32 v95, v223
	global_load_dwordx4 v[216:219], v[172:173], off offset:2304
	global_load_dwordx4 v[220:223], v[174:175], off offset:256
	v_lshlrev_b32_e32 v96, 16, v88
	v_and_b32_e32 v97, 0xffff0000, v88
	v_lshlrev_b32_e32 v98, 16, v92
	v_and_b32_e32 v99, 0xffff0000, v92
	v_lshlrev_b32_e32 v88, 16, v89
	v_and_b32_e32 v89, 0xffff0000, v89
	v_lshlrev_b32_e32 v92, 16, v93
	v_and_b32_e32 v93, 0xffff0000, v93
	v_pk_fma_f32 v[86:87], v[86:87], v[88:89], v[92:93]
	v_lshlrev_b32_e32 v88, 16, v90
	v_and_b32_e32 v89, 0xffff0000, v90
	v_lshlrev_b32_e32 v92, 16, v94
	v_and_b32_e32 v93, 0xffff0000, v94
	v_pk_fma_f32 v[88:89], v[80:81], v[88:89], v[92:93]
	v_lshlrev_b32_e32 v80, 16, v91
	v_and_b32_e32 v81, 0xffff0000, v91
	v_lshlrev_b32_e32 v90, 16, v95
	v_and_b32_e32 v91, 0xffff0000, v95
	v_pk_fma_f32 v[84:85], v[84:85], v[96:97], v[98:99]
	v_pk_fma_f32 v[90:91], v[82:83], v[80:81], v[90:91]
	v_cvt_pk_bf16_f32 v80, v84, v85
	v_cvt_pk_bf16_f32 v81, v86, v87
	v_cvt_pk_bf16_f32 v82, v88, v89
	v_cvt_pk_bf16_f32 v83, v90, v91
	global_store_dwordx4 v[106:107], v[80:83], off offset:256
	s_nop 1
	v_or_b32_e32 v80, 48, v140
	v_ashrrev_i32_e32 v81, 31, v80
	v_lshlrev_b64 v[82:83], 12, v[80:81]
	v_lshlrev_b64 v[84:85], 11, v[80:81]
	v_lshl_add_u64 v[80:81], s[42:43], 0, v[82:83]
	v_lshl_add_u64 v[84:85], s[40:41], 0, v[84:85]
	v_lshl_add_u64 v[88:89], v[80:81], 0, v[138:139]
	v_lshl_add_u64 v[90:91], v[84:85], 0, v[138:139]
	s_waitcnt vmcnt(10)
	s_nop 1
	v_mov_b32_e32 v80, v224
	v_mov_b32_e32 v81, v225
	v_mov_b32_e32 v82, v226
	v_mov_b32_e32 v83, v227
	v_mov_b32_e32 v84, v228
	v_mov_b32_e32 v85, v229
	v_mov_b32_e32 v86, v230
	v_mov_b32_e32 v87, v231
	v_lshl_add_u64 v[172:173], v[204:205], 1, v[172:173]
	v_lshl_add_u64 v[174:175], v[204:205], 0, v[174:175]
	global_load_dwordx4 v[224:227], v[172:173], off offset:2048
	global_load_dwordx4 v[228:231], v[174:175], off
	v_lshlrev_b32_e32 v92, 16, v80
	v_and_b32_e32 v93, 0xffff0000, v80
	v_lshlrev_b32_e32 v94, 16, v84
	v_and_b32_e32 v95, 0xffff0000, v84
	v_lshlrev_b32_e32 v80, 16, v81
	v_and_b32_e32 v81, 0xffff0000, v81
	v_lshlrev_b32_e32 v84, 16, v85
	v_and_b32_e32 v85, 0xffff0000, v85
	v_pk_fma_f32 v[78:79], v[78:79], v[80:81], v[84:85]
	v_lshlrev_b32_e32 v80, 16, v82
	v_and_b32_e32 v81, 0xffff0000, v82
	v_lshlrev_b32_e32 v84, 16, v86
	v_and_b32_e32 v85, 0xffff0000, v86
	v_pk_fma_f32 v[80:81], v[72:73], v[80:81], v[84:85]
	v_lshlrev_b32_e32 v72, 16, v83
	v_and_b32_e32 v73, 0xffff0000, v83
	v_lshlrev_b32_e32 v82, 16, v87
	v_and_b32_e32 v83, 0xffff0000, v87
	v_pk_fma_f32 v[76:77], v[76:77], v[92:93], v[94:95]
	v_pk_fma_f32 v[82:83], v[74:75], v[72:73], v[82:83]
	v_cvt_pk_bf16_f32 v72, v76, v77
	v_cvt_pk_bf16_f32 v73, v78, v79
	v_cvt_pk_bf16_f32 v74, v80, v81
	v_cvt_pk_bf16_f32 v75, v82, v83
	global_store_dwordx4 v[90:91], v[72:75], off
	s_nop 0
	s_waitcnt vmcnt(10)
	s_nop 1
	v_mov_b32_e32 v72, v232
	v_mov_b32_e32 v73, v233
	v_mov_b32_e32 v74, v234
	v_mov_b32_e32 v75, v235
	v_mov_b32_e32 v76, v236
	v_mov_b32_e32 v77, v237
	v_mov_b32_e32 v78, v238
	v_mov_b32_e32 v79, v239
	global_load_dwordx4 v[232:235], v[172:173], off offset:2304
	global_load_dwordx4 v[236:239], v[174:175], off offset:256
	v_lshlrev_b32_e32 v80, 16, v72
	v_and_b32_e32 v81, 0xffff0000, v72
	v_lshlrev_b32_e32 v82, 16, v76
	v_and_b32_e32 v83, 0xffff0000, v76
	v_lshlrev_b32_e32 v72, 16, v73
	v_and_b32_e32 v73, 0xffff0000, v73
	v_lshlrev_b32_e32 v76, 16, v77
	v_and_b32_e32 v77, 0xffff0000, v77
	v_pk_fma_f32 v[70:71], v[70:71], v[72:73], v[76:77]
	v_lshlrev_b32_e32 v72, 16, v74
	v_and_b32_e32 v73, 0xffff0000, v74
	v_lshlrev_b32_e32 v76, 16, v78
	v_and_b32_e32 v77, 0xffff0000, v78
	v_pk_fma_f32 v[72:73], v[64:65], v[72:73], v[76:77]
	v_lshlrev_b32_e32 v64, 16, v75
	v_and_b32_e32 v65, 0xffff0000, v75
	v_lshlrev_b32_e32 v74, 16, v79
	v_and_b32_e32 v75, 0xffff0000, v79
	v_pk_fma_f32 v[68:69], v[68:69], v[80:81], v[82:83]
	v_pk_fma_f32 v[74:75], v[66:67], v[64:65], v[74:75]
	v_cvt_pk_bf16_f32 v64, v68, v69
	v_cvt_pk_bf16_f32 v65, v70, v71
	v_cvt_pk_bf16_f32 v66, v72, v73
	v_cvt_pk_bf16_f32 v67, v74, v75
	global_store_dwordx4 v[90:91], v[64:67], off offset:256
	s_nop 1
	v_add_u32_e32 v64, 0x80, v140
	v_ashrrev_i32_e32 v65, 31, v64
	v_lshlrev_b64 v[66:67], 12, v[64:65]
	v_lshlrev_b64 v[68:69], 11, v[64:65]
	v_lshl_add_u64 v[64:65], s[42:43], 0, v[66:67]
	v_lshl_add_u64 v[68:69], s[40:41], 0, v[68:69]
	v_lshl_add_u64 v[72:73], v[64:65], 0, v[138:139]
	v_lshl_add_u64 v[74:75], v[68:69], 0, v[138:139]
	s_waitcnt vmcnt(10)
	s_nop 1
	v_mov_b32_e32 v64, v208
	v_mov_b32_e32 v65, v209
	v_mov_b32_e32 v66, v210
	v_mov_b32_e32 v67, v211
	v_mov_b32_e32 v68, v212
	v_mov_b32_e32 v69, v213
	v_mov_b32_e32 v70, v214
	v_mov_b32_e32 v71, v215
	v_lshl_add_u64 v[172:173], v[204:205], 1, v[172:173]
	v_lshl_add_u64 v[174:175], v[204:205], 0, v[174:175]
	global_load_dwordx4 v[208:211], v[172:173], off offset:2048
	global_load_dwordx4 v[212:215], v[174:175], off
	v_lshlrev_b32_e32 v76, 16, v64
	v_and_b32_e32 v77, 0xffff0000, v64
	v_lshlrev_b32_e32 v78, 16, v68
	v_and_b32_e32 v79, 0xffff0000, v68
	v_lshlrev_b32_e32 v64, 16, v65
	v_and_b32_e32 v65, 0xffff0000, v65
	v_lshlrev_b32_e32 v68, 16, v69
	v_and_b32_e32 v69, 0xffff0000, v69
	v_pk_fma_f32 v[62:63], v[62:63], v[64:65], v[68:69]
	v_lshlrev_b32_e32 v64, 16, v66
	v_and_b32_e32 v65, 0xffff0000, v66
	v_lshlrev_b32_e32 v68, 16, v70
	v_and_b32_e32 v69, 0xffff0000, v70
	v_pk_fma_f32 v[64:65], v[56:57], v[64:65], v[68:69]
	v_lshlrev_b32_e32 v56, 16, v67
	v_and_b32_e32 v57, 0xffff0000, v67
	v_lshlrev_b32_e32 v66, 16, v71
	v_and_b32_e32 v67, 0xffff0000, v71
	v_pk_fma_f32 v[60:61], v[60:61], v[76:77], v[78:79]
	v_pk_fma_f32 v[66:67], v[58:59], v[56:57], v[66:67]
	v_cvt_pk_bf16_f32 v56, v60, v61
	v_cvt_pk_bf16_f32 v57, v62, v63
	v_cvt_pk_bf16_f32 v58, v64, v65
	v_cvt_pk_bf16_f32 v59, v66, v67
	global_store_dwordx4 v[74:75], v[56:59], off
	s_nop 0
	s_waitcnt vmcnt(10)
	s_nop 1
	v_mov_b32_e32 v56, v216
	v_mov_b32_e32 v57, v217
	v_mov_b32_e32 v58, v218
	v_mov_b32_e32 v59, v219
	v_mov_b32_e32 v60, v220
	v_mov_b32_e32 v61, v221
	v_mov_b32_e32 v62, v222
	v_mov_b32_e32 v63, v223
	global_load_dwordx4 v[216:219], v[172:173], off offset:2304
	global_load_dwordx4 v[220:223], v[174:175], off offset:256
	v_lshlrev_b32_e32 v64, 16, v56
	v_and_b32_e32 v65, 0xffff0000, v56
	v_lshlrev_b32_e32 v66, 16, v60
	v_and_b32_e32 v67, 0xffff0000, v60
	v_lshlrev_b32_e32 v56, 16, v57
	v_and_b32_e32 v57, 0xffff0000, v57
	v_lshlrev_b32_e32 v60, 16, v61
	v_and_b32_e32 v61, 0xffff0000, v61
	v_pk_fma_f32 v[54:55], v[54:55], v[56:57], v[60:61]
	v_lshlrev_b32_e32 v56, 16, v58
	v_and_b32_e32 v57, 0xffff0000, v58
	v_lshlrev_b32_e32 v60, 16, v62
	v_and_b32_e32 v61, 0xffff0000, v62
	v_pk_fma_f32 v[56:57], v[48:49], v[56:57], v[60:61]
	v_lshlrev_b32_e32 v48, 16, v59
	v_and_b32_e32 v49, 0xffff0000, v59
	v_lshlrev_b32_e32 v58, 16, v63
	v_and_b32_e32 v59, 0xffff0000, v63
	v_pk_fma_f32 v[52:53], v[52:53], v[64:65], v[66:67]
	v_pk_fma_f32 v[58:59], v[50:51], v[48:49], v[58:59]
	v_cvt_pk_bf16_f32 v48, v52, v53
	v_cvt_pk_bf16_f32 v49, v54, v55
	v_cvt_pk_bf16_f32 v50, v56, v57
	v_cvt_pk_bf16_f32 v51, v58, v59
	global_store_dwordx4 v[74:75], v[48:51], off offset:256
	s_nop 1
	v_add_u32_e32 v48, 0x90, v140
	v_ashrrev_i32_e32 v49, 31, v48
	v_lshlrev_b64 v[50:51], 12, v[48:49]
	v_lshlrev_b64 v[52:53], 11, v[48:49]
	v_lshl_add_u64 v[48:49], s[42:43], 0, v[50:51]
	v_lshl_add_u64 v[52:53], s[40:41], 0, v[52:53]
	v_lshl_add_u64 v[56:57], v[48:49], 0, v[138:139]
	v_lshl_add_u64 v[58:59], v[52:53], 0, v[138:139]
	s_waitcnt vmcnt(10)
	s_nop 1
	v_mov_b32_e32 v48, v224
	v_mov_b32_e32 v49, v225
	v_mov_b32_e32 v50, v226
	v_mov_b32_e32 v51, v227
	v_mov_b32_e32 v52, v228
	v_mov_b32_e32 v53, v229
	v_mov_b32_e32 v54, v230
	v_mov_b32_e32 v55, v231
	v_lshl_add_u64 v[172:173], v[204:205], 1, v[172:173]
	v_lshl_add_u64 v[174:175], v[204:205], 0, v[174:175]
	global_load_dwordx4 v[224:227], v[172:173], off offset:2048
	global_load_dwordx4 v[228:231], v[174:175], off
	v_lshlrev_b32_e32 v60, 16, v48
	v_and_b32_e32 v61, 0xffff0000, v48
	v_lshlrev_b32_e32 v62, 16, v52
	v_and_b32_e32 v63, 0xffff0000, v52
	v_lshlrev_b32_e32 v48, 16, v49
	v_and_b32_e32 v49, 0xffff0000, v49
	v_lshlrev_b32_e32 v52, 16, v53
	v_and_b32_e32 v53, 0xffff0000, v53
	v_pk_fma_f32 v[46:47], v[46:47], v[48:49], v[52:53]
	v_lshlrev_b32_e32 v48, 16, v50
	v_and_b32_e32 v49, 0xffff0000, v50
	v_lshlrev_b32_e32 v52, 16, v54
	v_and_b32_e32 v53, 0xffff0000, v54
	v_pk_fma_f32 v[48:49], v[40:41], v[48:49], v[52:53]
	v_lshlrev_b32_e32 v40, 16, v51
	v_and_b32_e32 v41, 0xffff0000, v51
	v_lshlrev_b32_e32 v50, 16, v55
	v_and_b32_e32 v51, 0xffff0000, v55
	v_pk_fma_f32 v[44:45], v[44:45], v[60:61], v[62:63]
	v_pk_fma_f32 v[50:51], v[42:43], v[40:41], v[50:51]
	v_cvt_pk_bf16_f32 v40, v44, v45
	v_cvt_pk_bf16_f32 v41, v46, v47
	v_cvt_pk_bf16_f32 v42, v48, v49
	v_cvt_pk_bf16_f32 v43, v50, v51
	global_store_dwordx4 v[58:59], v[40:43], off
	s_nop 0
	s_waitcnt vmcnt(10)
	s_nop 1
	v_mov_b32_e32 v40, v232
	v_mov_b32_e32 v41, v233
	v_mov_b32_e32 v42, v234
	v_mov_b32_e32 v43, v235
	v_mov_b32_e32 v44, v236
	v_mov_b32_e32 v45, v237
	v_mov_b32_e32 v46, v238
	v_mov_b32_e32 v47, v239
	global_load_dwordx4 v[232:235], v[172:173], off offset:2304
	global_load_dwordx4 v[236:239], v[174:175], off offset:256
	v_lshlrev_b32_e32 v48, 16, v40
	v_and_b32_e32 v49, 0xffff0000, v40
	v_lshlrev_b32_e32 v50, 16, v44
	v_and_b32_e32 v51, 0xffff0000, v44
	v_lshlrev_b32_e32 v40, 16, v41
	v_and_b32_e32 v41, 0xffff0000, v41
	v_lshlrev_b32_e32 v44, 16, v45
	v_and_b32_e32 v45, 0xffff0000, v45
	v_pk_fma_f32 v[38:39], v[38:39], v[40:41], v[44:45]
	v_lshlrev_b32_e32 v40, 16, v42
	v_and_b32_e32 v41, 0xffff0000, v42
	v_lshlrev_b32_e32 v44, 16, v46
	v_and_b32_e32 v45, 0xffff0000, v46
	v_pk_fma_f32 v[40:41], v[32:33], v[40:41], v[44:45]
	v_lshlrev_b32_e32 v32, 16, v43
	v_and_b32_e32 v33, 0xffff0000, v43
	v_lshlrev_b32_e32 v42, 16, v47
	v_and_b32_e32 v43, 0xffff0000, v47
	v_pk_fma_f32 v[36:37], v[36:37], v[48:49], v[50:51]
	v_pk_fma_f32 v[42:43], v[34:35], v[32:33], v[42:43]
	v_cvt_pk_bf16_f32 v32, v36, v37
	v_cvt_pk_bf16_f32 v33, v38, v39
	v_cvt_pk_bf16_f32 v34, v40, v41
	v_cvt_pk_bf16_f32 v35, v42, v43
	global_store_dwordx4 v[58:59], v[32:35], off offset:256
	s_nop 1
	v_add_u32_e32 v32, 0xa0, v140
	v_ashrrev_i32_e32 v33, 31, v32
	v_lshlrev_b64 v[34:35], 12, v[32:33]
	v_lshlrev_b64 v[36:37], 11, v[32:33]
	v_lshl_add_u64 v[32:33], s[42:43], 0, v[34:35]
	v_lshl_add_u64 v[36:37], s[40:41], 0, v[36:37]
	v_lshl_add_u64 v[40:41], v[32:33], 0, v[138:139]
	v_lshl_add_u64 v[42:43], v[36:37], 0, v[138:139]
	s_waitcnt vmcnt(10)
	s_nop 1
	v_mov_b32_e32 v32, v208
	v_mov_b32_e32 v33, v209
	v_mov_b32_e32 v34, v210
	v_mov_b32_e32 v35, v211
	v_mov_b32_e32 v36, v212
	v_mov_b32_e32 v37, v213
	v_mov_b32_e32 v38, v214
	v_mov_b32_e32 v39, v215
	v_lshlrev_b32_e32 v44, 16, v32
	v_and_b32_e32 v45, 0xffff0000, v32
	v_lshlrev_b32_e32 v46, 16, v36
	v_and_b32_e32 v47, 0xffff0000, v36
	v_lshlrev_b32_e32 v32, 16, v33
	v_and_b32_e32 v33, 0xffff0000, v33
	v_lshlrev_b32_e32 v36, 16, v37
	v_and_b32_e32 v37, 0xffff0000, v37
	v_pk_fma_f32 v[30:31], v[30:31], v[32:33], v[36:37]
	v_lshlrev_b32_e32 v32, 16, v34
	v_and_b32_e32 v33, 0xffff0000, v34
	v_lshlrev_b32_e32 v36, 16, v38
	v_and_b32_e32 v37, 0xffff0000, v38
	v_pk_fma_f32 v[32:33], v[24:25], v[32:33], v[36:37]
	v_lshlrev_b32_e32 v24, 16, v35
	v_and_b32_e32 v25, 0xffff0000, v35
	v_lshlrev_b32_e32 v34, 16, v39
	v_and_b32_e32 v35, 0xffff0000, v39
	v_pk_fma_f32 v[28:29], v[28:29], v[44:45], v[46:47]
	v_pk_fma_f32 v[34:35], v[26:27], v[24:25], v[34:35]
	v_cvt_pk_bf16_f32 v24, v28, v29
	v_cvt_pk_bf16_f32 v25, v30, v31
	v_cvt_pk_bf16_f32 v26, v32, v33
	v_cvt_pk_bf16_f32 v27, v34, v35
	global_store_dwordx4 v[42:43], v[24:27], off
	s_nop 0
	s_waitcnt vmcnt(8)
	s_nop 1
	v_mov_b32_e32 v24, v216
	v_mov_b32_e32 v25, v217
	v_mov_b32_e32 v26, v218
	v_mov_b32_e32 v27, v219
	v_mov_b32_e32 v28, v220
	v_mov_b32_e32 v29, v221
	v_mov_b32_e32 v30, v222
	v_mov_b32_e32 v31, v223
	v_lshlrev_b32_e32 v32, 16, v24
	v_and_b32_e32 v33, 0xffff0000, v24
	v_lshlrev_b32_e32 v34, 16, v28
	v_and_b32_e32 v35, 0xffff0000, v28
	v_lshlrev_b32_e32 v24, 16, v25
	v_and_b32_e32 v25, 0xffff0000, v25
	v_lshlrev_b32_e32 v28, 16, v29
	v_and_b32_e32 v29, 0xffff0000, v29
	v_pk_fma_f32 v[22:23], v[22:23], v[24:25], v[28:29]
	v_lshlrev_b32_e32 v24, 16, v26
	v_and_b32_e32 v25, 0xffff0000, v26
	v_lshlrev_b32_e32 v28, 16, v30
	v_and_b32_e32 v29, 0xffff0000, v30
	v_pk_fma_f32 v[24:25], v[16:17], v[24:25], v[28:29]
	v_lshlrev_b32_e32 v16, 16, v27
	v_and_b32_e32 v17, 0xffff0000, v27
	v_lshlrev_b32_e32 v26, 16, v31
	v_and_b32_e32 v27, 0xffff0000, v31
	v_pk_fma_f32 v[20:21], v[20:21], v[32:33], v[34:35]
	v_pk_fma_f32 v[26:27], v[18:19], v[16:17], v[26:27]
	v_cvt_pk_bf16_f32 v16, v20, v21
	v_cvt_pk_bf16_f32 v17, v22, v23
	v_cvt_pk_bf16_f32 v18, v24, v25
	v_cvt_pk_bf16_f32 v19, v26, v27
	global_store_dwordx4 v[42:43], v[16:19], off offset:256
	s_nop 1
	v_add_u32_e32 v16, 0xb0, v140
	v_ashrrev_i32_e32 v17, 31, v16
	v_lshlrev_b64 v[18:19], 12, v[16:17]
	v_lshlrev_b64 v[20:21], 11, v[16:17]
	v_lshl_add_u64 v[16:17], s[42:43], 0, v[18:19]
	v_lshl_add_u64 v[20:21], s[40:41], 0, v[20:21]
	v_lshl_add_u64 v[24:25], v[16:17], 0, v[138:139]
	v_lshl_add_u64 v[26:27], v[20:21], 0, v[138:139]
	s_waitcnt vmcnt(6)
	s_nop 1
	v_mov_b32_e32 v16, v224
	v_mov_b32_e32 v17, v225
	v_mov_b32_e32 v18, v226
	v_mov_b32_e32 v19, v227
	v_mov_b32_e32 v20, v228
	v_mov_b32_e32 v21, v229
	v_mov_b32_e32 v22, v230
	v_mov_b32_e32 v23, v231
	v_lshlrev_b32_e32 v28, 16, v16
	v_and_b32_e32 v29, 0xffff0000, v16
	v_lshlrev_b32_e32 v30, 16, v20
	v_and_b32_e32 v31, 0xffff0000, v20
	v_lshlrev_b32_e32 v16, 16, v17
	v_and_b32_e32 v17, 0xffff0000, v17
	v_lshlrev_b32_e32 v20, 16, v21
	v_and_b32_e32 v21, 0xffff0000, v21
	v_pk_fma_f32 v[14:15], v[14:15], v[16:17], v[20:21]
	v_lshlrev_b32_e32 v16, 16, v18
	v_and_b32_e32 v17, 0xffff0000, v18
	v_lshlrev_b32_e32 v20, 16, v22
	v_and_b32_e32 v21, 0xffff0000, v22
	v_pk_fma_f32 v[16:17], v[8:9], v[16:17], v[20:21]
	v_lshlrev_b32_e32 v8, 16, v19
	v_and_b32_e32 v9, 0xffff0000, v19
	v_lshlrev_b32_e32 v18, 16, v23
	v_and_b32_e32 v19, 0xffff0000, v23
	v_pk_fma_f32 v[12:13], v[12:13], v[28:29], v[30:31]
	v_pk_fma_f32 v[18:19], v[10:11], v[8:9], v[18:19]
	v_cvt_pk_bf16_f32 v8, v12, v13
	v_cvt_pk_bf16_f32 v9, v14, v15
	v_cvt_pk_bf16_f32 v10, v16, v17
	v_cvt_pk_bf16_f32 v11, v18, v19
	global_store_dwordx4 v[26:27], v[8:11], off
	s_nop 0
	s_waitcnt vmcnt(4)
	s_nop 1
	v_mov_b32_e32 v8, v232
	v_mov_b32_e32 v9, v233
	v_mov_b32_e32 v10, v234
	v_mov_b32_e32 v11, v235
	v_mov_b32_e32 v12, v236
	v_mov_b32_e32 v13, v237
	v_mov_b32_e32 v14, v238
	v_mov_b32_e32 v15, v239
	v_lshlrev_b32_e32 v16, 16, v8
	v_and_b32_e32 v17, 0xffff0000, v8
	v_lshlrev_b32_e32 v18, 16, v12
	v_and_b32_e32 v19, 0xffff0000, v12
	v_lshlrev_b32_e32 v8, 16, v9
	v_and_b32_e32 v9, 0xffff0000, v9
	v_lshlrev_b32_e32 v12, 16, v13
	v_and_b32_e32 v13, 0xffff0000, v13
	v_pk_fma_f32 v[6:7], v[6:7], v[8:9], v[12:13]
	v_lshlrev_b32_e32 v8, 16, v10
	v_and_b32_e32 v9, 0xffff0000, v10
	v_lshlrev_b32_e32 v12, 16, v14
	v_and_b32_e32 v13, 0xffff0000, v14
	v_pk_fma_f32 v[8:9], v[0:1], v[8:9], v[12:13]
	v_lshlrev_b32_e32 v0, 16, v11
	v_and_b32_e32 v1, 0xffff0000, v11
	v_lshlrev_b32_e32 v10, 16, v15
	v_and_b32_e32 v11, 0xffff0000, v15
	v_pk_fma_f32 v[4:5], v[4:5], v[16:17], v[18:19]
	v_pk_fma_f32 v[10:11], v[2:3], v[0:1], v[10:11]
	v_cvt_pk_bf16_f32 v0, v4, v5
	v_cvt_pk_bf16_f32 v1, v6, v7
	v_cvt_pk_bf16_f32 v2, v8, v9
	v_cvt_pk_bf16_f32 v3, v10, v11
	global_store_dwordx4 v[26:27], v[0:3], off offset:256
	s_cbranch_vccnz .LBB0_1109
	s_andn2_b64 vcc, exec, s[0:1]
	s_cbranch_vccnz .LBB0_1108
	s_barrier
	s_branch .LBB0_1108
